# scan patch + K-loops: all s_setprio flips deleted, no static raise
# speedup vs baseline: 1.0071x; 1.0019x over previous
.LBB0_132:
	s_add_u32 s36, s34, 0xfff00080
	s_addc_u32 s37, s35, -1
	s_add_i32 s68, 0, 0x10000
	s_cmp_eq_u32 s67, 60
	s_cselect_b32 s41, s25, s37
	s_cselect_b32 s40, s61, s36
	v_add_u32_e32 v144, s68, v147
	s_cselect_b32 s37, s23, s66
	s_cselect_b32 s36, s62, s63
	s_add_i32 s70, 0, 0x14000
	s_waitcnt lgkmcnt(0)
	ds_read_b128 v[152:155], v144
	ds_read_b128 v[156:159], v144 offset:1024
	ds_read_b128 v[160:163], v144 offset:2048
	ds_read_b128 v[164:167], v144 offset:3072
	v_add_u32_e32 v144, s70, v147
	ds_read_b128 v[168:171], v144
	ds_read_b128 v[172:175], v144 offset:1024
	ds_read_b128 v[176:179], v144 offset:2048
	ds_read_b128 v[180:183], v144 offset:3072
	v_lshl_add_u64 v[212:213], s[34:35], 0, v[140:141]
	s_add_i32 m0, s51, 0xc000
	ds_read_b128 v[184:187], v151
	ds_read_b128 v[188:191], v151 offset:1024
	ds_read_b128 v[192:195], v151 offset:2048
	ds_read_b128 v[196:199], v151 offset:3072
	ds_read_b128 v[200:203], v151 offset:4096
	ds_read_b128 v[204:207], v151 offset:5120
	ds_read_b128 v[208:211], v151 offset:6144
	ds_read_b128 v[216:219], v151 offset:7168
	global_load_lds_dwordx4 v[212:213], off
	v_lshl_add_u64 v[212:213], s[34:35], 0, v[142:143]
	s_add_i32 m0, s51, 0xe000
	s_nop 0
	global_load_lds_dwordx4 v[212:213], off
	s_waitcnt vmcnt(8)
	s_waitcnt lgkmcnt(0)
	s_barrier
	s_waitcnt lgkmcnt(0)
	v_mfma_f32_16x16x32_bf16 v[82:85], v[152:155], v[184:187], v[82:85]
	v_mfma_f32_16x16x32_bf16 v[74:77], v[160:163], v[184:187], v[74:77]
	v_mfma_f32_16x16x32_bf16 v[70:73], v[152:155], v[192:195], v[70:73]
	v_mfma_f32_16x16x32_bf16 v[62:65], v[160:163], v[192:195], v[62:65]
	v_mfma_f32_16x16x32_bf16 v[54:57], v[152:155], v[200:203], v[54:57]
	v_mfma_f32_16x16x32_bf16 v[50:53], v[160:163], v[200:203], v[50:53]
	v_mfma_f32_16x16x32_bf16 v[38:41], v[152:155], v[208:211], v[38:41]
	v_mfma_f32_16x16x32_bf16 v[34:37], v[160:163], v[208:211], v[34:37]
	v_mfma_f32_16x16x32_bf16 v[82:85], v[156:159], v[188:191], v[82:85]
	v_mfma_f32_16x16x32_bf16 v[74:77], v[164:167], v[188:191], v[74:77]
	v_mfma_f32_16x16x32_bf16 v[70:73], v[156:159], v[196:199], v[70:73]
	v_mfma_f32_16x16x32_bf16 v[62:65], v[164:167], v[196:199], v[62:65]
	v_mfma_f32_16x16x32_bf16 v[54:57], v[156:159], v[204:207], v[54:57]
	v_mfma_f32_16x16x32_bf16 v[50:53], v[164:167], v[204:207], v[50:53]
	v_mfma_f32_16x16x32_bf16 v[38:41], v[156:159], v[216:219], v[38:41]
	v_mfma_f32_16x16x32_bf16 v[34:37], v[164:167], v[216:219], v[34:37]
	v_mfma_f32_16x16x32_bf16 v[126:129], v[168:171], v[184:187], v[126:129]
	v_mfma_f32_16x16x32_bf16 v[122:125], v[176:179], v[184:187], v[122:125]
	v_mfma_f32_16x16x32_bf16 v[118:121], v[168:171], v[192:195], v[118:121]
	v_mfma_f32_16x16x32_bf16 v[114:117], v[176:179], v[192:195], v[114:117]
	v_mfma_f32_16x16x32_bf16 v[110:113], v[168:171], v[200:203], v[110:113]
	v_mfma_f32_16x16x32_bf16 v[106:109], v[176:179], v[200:203], v[106:109]
	v_mfma_f32_16x16x32_bf16 v[102:105], v[168:171], v[208:211], v[102:105]
	v_mfma_f32_16x16x32_bf16 v[98:101], v[176:179], v[208:211], v[98:101]
	v_mfma_f32_16x16x32_bf16 v[126:129], v[172:175], v[188:191], v[126:129]
	v_mfma_f32_16x16x32_bf16 v[122:125], v[180:183], v[188:191], v[122:125]
	v_mfma_f32_16x16x32_bf16 v[118:121], v[172:175], v[196:199], v[118:121]
	v_mfma_f32_16x16x32_bf16 v[114:117], v[180:183], v[196:199], v[114:117]
	v_mfma_f32_16x16x32_bf16 v[110:113], v[172:175], v[204:207], v[110:113]
	v_mfma_f32_16x16x32_bf16 v[106:109], v[180:183], v[204:207], v[106:109]
	v_mfma_f32_16x16x32_bf16 v[102:105], v[172:175], v[216:219], v[102:105]
	v_mfma_f32_16x16x32_bf16 v[98:101], v[180:183], v[216:219], v[98:101]
	s_barrier
	s_add_i32 s68, s68, s50
	v_lshl_add_u64 v[212:213], s[36:37], 0, v[130:131]
	s_mov_b32 m0, s68
	ds_read_b128 v[184:187], v151 offset:16384
	ds_read_b128 v[188:191], v151 offset:17408
	ds_read_b128 v[192:195], v151 offset:18432
	ds_read_b128 v[196:199], v151 offset:19456
	ds_read_b128 v[200:203], v151 offset:20480
	ds_read_b128 v[204:207], v151 offset:21504
	ds_read_b128 v[208:211], v151 offset:22528
	ds_read_b128 v[216:219], v151 offset:23552
	global_load_lds_dwordx4 v[212:213], off
	s_add_i32 m0, s68, 0x2000
	s_add_u32 s68, s36, 0x100000
	v_lshl_add_u64 v[220:221], s[36:37], 0, v[132:133]
	s_addc_u32 s69, s37, 0
	s_add_i32 s70, s70, s50
	global_load_lds_dwordx4 v[220:221], off
	v_lshl_add_u64 v[222:223], s[68:69], 0, v[130:131]
	s_mov_b32 m0, s70
	v_lshl_add_u64 v[224:225], s[40:41], 0, v[134:135]
	global_load_lds_dwordx4 v[222:223], off
	v_lshl_add_u64 v[222:223], s[68:69], 0, v[132:133]
	s_add_i32 m0, s70, 0x2000
	s_nop 0
	global_load_lds_dwordx4 v[222:223], off
	v_lshl_add_u64 v[222:223], s[40:41], 0, v[136:137]
	s_mov_b32 m0, s51
	s_nop 0
	global_load_lds_dwordx4 v[222:223], off
	s_mov_b32 m0, s52
	s_nop 0
	global_load_lds_dwordx4 v[224:225], off
	s_waitcnt vmcnt(8)
	s_waitcnt lgkmcnt(0)
	s_barrier
	s_waitcnt lgkmcnt(0)
	v_mfma_f32_16x16x32_bf16 v[30:33], v[152:155], v[184:187], v[30:33]
	v_mfma_f32_16x16x32_bf16 v[26:29], v[160:163], v[184:187], v[26:29]
	v_mfma_f32_16x16x32_bf16 v[22:25], v[152:155], v[192:195], v[22:25]
	v_mfma_f32_16x16x32_bf16 v[18:21], v[160:163], v[192:195], v[18:21]
	v_mfma_f32_16x16x32_bf16 v[14:17], v[152:155], v[200:203], v[14:17]
	v_mfma_f32_16x16x32_bf16 v[10:13], v[160:163], v[200:203], v[10:13]
	v_mfma_f32_16x16x32_bf16 v[6:9], v[152:155], v[208:211], v[6:9]
	v_mfma_f32_16x16x32_bf16 v[2:5], v[160:163], v[208:211], v[2:5]
	v_mfma_f32_16x16x32_bf16 v[30:33], v[156:159], v[188:191], v[30:33]
	v_mfma_f32_16x16x32_bf16 v[26:29], v[164:167], v[188:191], v[26:29]
	v_mfma_f32_16x16x32_bf16 v[22:25], v[156:159], v[196:199], v[22:25]
	v_mfma_f32_16x16x32_bf16 v[18:21], v[164:167], v[196:199], v[18:21]
	v_mfma_f32_16x16x32_bf16 v[14:17], v[156:159], v[204:207], v[14:17]
	v_mfma_f32_16x16x32_bf16 v[10:13], v[164:167], v[204:207], v[10:13]
	v_mfma_f32_16x16x32_bf16 v[6:9], v[156:159], v[216:219], v[6:9]
	v_mfma_f32_16x16x32_bf16 v[2:5], v[164:167], v[216:219], v[2:5]
	v_mfma_f32_16x16x32_bf16 v[94:97], v[168:171], v[184:187], v[94:97]
	v_mfma_f32_16x16x32_bf16 v[90:93], v[176:179], v[184:187], v[90:93]
	v_mfma_f32_16x16x32_bf16 v[86:89], v[168:171], v[192:195], v[86:89]
	v_mfma_f32_16x16x32_bf16 v[78:81], v[176:179], v[192:195], v[78:81]
	v_mfma_f32_16x16x32_bf16 v[66:69], v[168:171], v[200:203], v[66:69]
	v_mfma_f32_16x16x32_bf16 v[58:61], v[176:179], v[200:203], v[58:61]
	v_mfma_f32_16x16x32_bf16 v[46:49], v[168:171], v[208:211], v[46:49]
	v_mfma_f32_16x16x32_bf16 v[42:45], v[176:179], v[208:211], v[42:45]
	v_mfma_f32_16x16x32_bf16 v[94:97], v[172:175], v[188:191], v[94:97]
	v_mfma_f32_16x16x32_bf16 v[90:93], v[180:183], v[188:191], v[90:93]
	v_mfma_f32_16x16x32_bf16 v[86:89], v[172:175], v[196:199], v[86:89]
	v_mfma_f32_16x16x32_bf16 v[78:81], v[180:183], v[196:199], v[78:81]
	v_mfma_f32_16x16x32_bf16 v[66:69], v[172:175], v[204:207], v[66:69]
	v_mfma_f32_16x16x32_bf16 v[58:61], v[180:183], v[204:207], v[58:61]
	v_mfma_f32_16x16x32_bf16 v[46:49], v[172:175], v[216:219], v[46:49]
	v_mfma_f32_16x16x32_bf16 v[42:45], v[180:183], v[216:219], v[42:45]
	s_barrier
	s_add_i32 s68, 0, 0x18000
	v_add_u32_e32 v144, s68, v147
	s_add_i32 s69, 0, 0x1c000
	ds_read_b128 v[152:155], v144
	ds_read_b128 v[156:159], v144 offset:1024
	ds_read_b128 v[160:163], v144 offset:2048
	ds_read_b128 v[164:167], v144 offset:3072
	v_add_u32_e32 v144, s69, v147
	ds_read_b128 v[168:171], v144
	ds_read_b128 v[172:175], v144 offset:1024
	ds_read_b128 v[176:179], v144 offset:2048
	ds_read_b128 v[180:183], v144 offset:3072
	s_add_u32 s40, s40, 0x100000
	s_addc_u32 s41, s41, 0
	s_mov_b32 m0, s53
	v_lshl_add_u64 v[226:227], s[40:41], 0, v[136:137]
	ds_read_b128 v[184:187], v151 offset:32768
	ds_read_b128 v[188:191], v151 offset:33792
	ds_read_b128 v[192:195], v151 offset:34816
	ds_read_b128 v[196:199], v151 offset:35840
	ds_read_b128 v[200:203], v151 offset:36864
	ds_read_b128 v[204:207], v151 offset:37888
	ds_read_b128 v[208:211], v151 offset:38912
	ds_read_b128 v[216:219], v151 offset:39936
	global_load_lds_dwordx4 v[226:227], off
	v_lshl_add_u64 v[226:227], s[40:41], 0, v[134:135]
	s_mov_b32 m0, s54
	s_nop 0
	global_load_lds_dwordx4 v[226:227], off
	s_waitcnt vmcnt(8)
	s_waitcnt lgkmcnt(0)
	s_barrier
	s_waitcnt lgkmcnt(0)
	v_mfma_f32_16x16x32_bf16 v[82:85], v[152:155], v[184:187], v[82:85]
	v_mfma_f32_16x16x32_bf16 v[74:77], v[160:163], v[184:187], v[74:77]
	v_mfma_f32_16x16x32_bf16 v[70:73], v[152:155], v[192:195], v[70:73]
	v_mfma_f32_16x16x32_bf16 v[62:65], v[160:163], v[192:195], v[62:65]
	v_mfma_f32_16x16x32_bf16 v[54:57], v[152:155], v[200:203], v[54:57]
	v_mfma_f32_16x16x32_bf16 v[50:53], v[160:163], v[200:203], v[50:53]
	v_mfma_f32_16x16x32_bf16 v[38:41], v[152:155], v[208:211], v[38:41]
	v_mfma_f32_16x16x32_bf16 v[34:37], v[160:163], v[208:211], v[34:37]
	v_mfma_f32_16x16x32_bf16 v[82:85], v[156:159], v[188:191], v[82:85]
	v_mfma_f32_16x16x32_bf16 v[74:77], v[164:167], v[188:191], v[74:77]
	v_mfma_f32_16x16x32_bf16 v[70:73], v[156:159], v[196:199], v[70:73]
	v_mfma_f32_16x16x32_bf16 v[62:65], v[164:167], v[196:199], v[62:65]
	v_mfma_f32_16x16x32_bf16 v[54:57], v[156:159], v[204:207], v[54:57]
	v_mfma_f32_16x16x32_bf16 v[50:53], v[164:167], v[204:207], v[50:53]
	v_mfma_f32_16x16x32_bf16 v[38:41], v[156:159], v[216:219], v[38:41]
	v_mfma_f32_16x16x32_bf16 v[34:37], v[164:167], v[216:219], v[34:37]
	v_mfma_f32_16x16x32_bf16 v[126:129], v[168:171], v[184:187], v[126:129]
	v_mfma_f32_16x16x32_bf16 v[122:125], v[176:179], v[184:187], v[122:125]
	v_mfma_f32_16x16x32_bf16 v[118:121], v[168:171], v[192:195], v[118:121]
	v_mfma_f32_16x16x32_bf16 v[114:117], v[176:179], v[192:195], v[114:117]
	v_mfma_f32_16x16x32_bf16 v[110:113], v[168:171], v[200:203], v[110:113]
	v_mfma_f32_16x16x32_bf16 v[106:109], v[176:179], v[200:203], v[106:109]
	v_mfma_f32_16x16x32_bf16 v[102:105], v[168:171], v[208:211], v[102:105]
	v_mfma_f32_16x16x32_bf16 v[98:101], v[176:179], v[208:211], v[98:101]
	v_mfma_f32_16x16x32_bf16 v[126:129], v[172:175], v[188:191], v[126:129]
	v_mfma_f32_16x16x32_bf16 v[122:125], v[180:183], v[188:191], v[122:125]
	v_mfma_f32_16x16x32_bf16 v[118:121], v[172:175], v[196:199], v[118:121]
	v_mfma_f32_16x16x32_bf16 v[114:117], v[180:183], v[196:199], v[114:117]
	v_mfma_f32_16x16x32_bf16 v[110:113], v[172:175], v[204:207], v[110:113]
	v_mfma_f32_16x16x32_bf16 v[106:109], v[180:183], v[204:207], v[106:109]
	v_mfma_f32_16x16x32_bf16 v[102:105], v[172:175], v[216:219], v[102:105]
	v_mfma_f32_16x16x32_bf16 v[98:101], v[180:183], v[216:219], v[98:101]
	s_barrier
	s_add_i32 s40, s68, s50
	v_lshl_add_u64 v[212:213], v[212:213], 0, s[18:19]
	s_mov_b32 m0, s40
	ds_read_b128 v[184:187], v151 offset:49152
	ds_read_b128 v[188:191], v151 offset:50176
	ds_read_b128 v[192:195], v151 offset:51200
	ds_read_b128 v[196:199], v151 offset:52224
	ds_read_b128 v[200:203], v151 offset:53248
	ds_read_b128 v[204:207], v151 offset:54272
	ds_read_b128 v[208:211], v151 offset:55296
	ds_read_b128 v[216:219], v151 offset:56320
	global_load_lds_dwordx4 v[212:213], off
	s_add_i32 m0, s40, 0x2000
	s_add_u32 s36, s36, 0x100080
	v_lshl_add_u64 v[212:213], v[220:221], 0, s[18:19]
	s_addc_u32 s37, s37, 0
	s_add_i32 s40, s69, s50
	global_load_lds_dwordx4 v[212:213], off
	v_lshl_add_u64 v[212:213], s[36:37], 0, v[130:131]
	s_mov_b32 m0, s40
	s_nop 0
	global_load_lds_dwordx4 v[212:213], off
	v_lshl_add_u64 v[212:213], s[36:37], 0, v[132:133]
	s_add_i32 m0, s40, 0x2000
	s_nop 0
	global_load_lds_dwordx4 v[212:213], off
	v_lshl_add_u64 v[212:213], v[222:223], 0, s[18:19]
	s_mov_b32 m0, s30
	s_nop 0
	global_load_lds_dwordx4 v[212:213], off
	v_lshl_add_u64 v[212:213], v[224:225], 0, s[18:19]
	s_mov_b32 m0, s55
	s_nop 0
	global_load_lds_dwordx4 v[212:213], off
	s_waitcnt vmcnt(8)
	s_waitcnt lgkmcnt(0)
	s_barrier
	s_waitcnt lgkmcnt(0)
	v_mfma_f32_16x16x32_bf16 v[30:33], v[152:155], v[184:187], v[30:33]
	v_mfma_f32_16x16x32_bf16 v[26:29], v[160:163], v[184:187], v[26:29]
	v_mfma_f32_16x16x32_bf16 v[22:25], v[152:155], v[192:195], v[22:25]
	v_mfma_f32_16x16x32_bf16 v[18:21], v[160:163], v[192:195], v[18:21]
	v_mfma_f32_16x16x32_bf16 v[14:17], v[152:155], v[200:203], v[14:17]
	v_mfma_f32_16x16x32_bf16 v[10:13], v[160:163], v[200:203], v[10:13]
	v_mfma_f32_16x16x32_bf16 v[6:9], v[152:155], v[208:211], v[6:9]
	v_mfma_f32_16x16x32_bf16 v[2:5], v[160:163], v[208:211], v[2:5]
	v_mfma_f32_16x16x32_bf16 v[30:33], v[156:159], v[188:191], v[30:33]
	v_mfma_f32_16x16x32_bf16 v[26:29], v[164:167], v[188:191], v[26:29]
	v_mfma_f32_16x16x32_bf16 v[22:25], v[156:159], v[196:199], v[22:25]
	v_mfma_f32_16x16x32_bf16 v[18:21], v[164:167], v[196:199], v[18:21]
	v_mfma_f32_16x16x32_bf16 v[14:17], v[156:159], v[204:207], v[14:17]
	v_mfma_f32_16x16x32_bf16 v[10:13], v[164:167], v[204:207], v[10:13]
	v_mfma_f32_16x16x32_bf16 v[6:9], v[156:159], v[216:219], v[6:9]
	v_mfma_f32_16x16x32_bf16 v[2:5], v[164:167], v[216:219], v[2:5]
	v_mfma_f32_16x16x32_bf16 v[94:97], v[168:171], v[184:187], v[94:97]
	v_mfma_f32_16x16x32_bf16 v[90:93], v[176:179], v[184:187], v[90:93]
	v_mfma_f32_16x16x32_bf16 v[86:89], v[168:171], v[192:195], v[86:89]
	v_mfma_f32_16x16x32_bf16 v[78:81], v[176:179], v[192:195], v[78:81]
	v_mfma_f32_16x16x32_bf16 v[66:69], v[168:171], v[200:203], v[66:69]
	v_mfma_f32_16x16x32_bf16 v[58:61], v[176:179], v[200:203], v[58:61]
	v_mfma_f32_16x16x32_bf16 v[46:49], v[168:171], v[208:211], v[46:49]
	v_mfma_f32_16x16x32_bf16 v[42:45], v[176:179], v[208:211], v[42:45]
	v_mfma_f32_16x16x32_bf16 v[94:97], v[172:175], v[188:191], v[94:97]
	v_mfma_f32_16x16x32_bf16 v[90:93], v[180:183], v[188:191], v[90:93]
	v_mfma_f32_16x16x32_bf16 v[86:89], v[172:175], v[196:199], v[86:89]
	v_mfma_f32_16x16x32_bf16 v[78:81], v[180:183], v[196:199], v[78:81]
	v_mfma_f32_16x16x32_bf16 v[66:69], v[172:175], v[204:207], v[66:69]
	v_mfma_f32_16x16x32_bf16 v[58:61], v[180:183], v[204:207], v[58:61]
	v_mfma_f32_16x16x32_bf16 v[46:49], v[172:175], v[216:219], v[46:49]
	v_mfma_f32_16x16x32_bf16 v[42:45], v[180:183], v[216:219], v[42:45]
	s_barrier
	s_add_i32 s67, s67, 2
	s_add_u32 s34, s34, 0x100
	s_addc_u32 s35, s35, 0
	s_add_u32 s63, s63, 0x100
	s_addc_u32 s66, s66, 0
	s_cmp_gt_u32 s67, 61
	s_cbranch_scc0 .LBB0_132
	s_and_b64 vcc, exec, s[12:13]
	s_cbranch_vccz .LBB0_135
	s_barrier

.LBB0_872:
	s_add_u32 s26, s24, 0xfff00080
	s_addc_u32 s27, s25, -1
	s_add_i32 s56, 0, 0x10000
	s_cmp_eq_u32 s55, 60
	s_cselect_b32 s29, s13, s27
	s_cselect_b32 s28, s51, s26
	v_add_u32_e32 v148, s56, v152
	s_cselect_b32 s27, s9, s54
	s_cselect_b32 s26, s52, s53
	s_add_i32 s58, 0, 0x14000
	ds_read_b128 v[144:147], v148
	ds_read_b128 v[156:159], v148 offset:1024
	ds_read_b128 v[160:163], v148 offset:2048
	ds_read_b128 v[164:167], v148 offset:3072
	v_add_u32_e32 v148, s58, v152
	ds_read_b128 v[168:171], v148
	ds_read_b128 v[172:175], v148 offset:1024
	ds_read_b128 v[176:179], v148 offset:2048
	ds_read_b128 v[180:183], v148 offset:3072
	v_lshl_add_u64 v[148:149], s[24:25], 0, v[140:141]
	s_add_i32 m0, s41, 0xc000
	ds_read_b128 v[184:187], v154
	ds_read_b128 v[188:191], v154 offset:1024
	ds_read_b128 v[192:195], v154 offset:2048
	ds_read_b128 v[196:199], v154 offset:3072
	ds_read_b128 v[200:203], v154 offset:4096
	ds_read_b128 v[204:207], v154 offset:5120
	ds_read_b128 v[208:211], v154 offset:6144
	ds_read_b128 v[216:219], v154 offset:7168
	global_load_lds_dwordx4 v[148:149], off
	v_lshl_add_u64 v[148:149], s[24:25], 0, v[142:143]
	s_add_i32 m0, s41, 0xe000
	s_nop 0
	global_load_lds_dwordx4 v[148:149], off
	s_waitcnt vmcnt(8)
	s_waitcnt lgkmcnt(0)
	s_barrier
	s_waitcnt lgkmcnt(0)
	v_mfma_f32_16x16x32_bf16 v[126:129], v[144:147], v[184:187], v[126:129]
	v_mfma_f32_16x16x32_bf16 v[122:125], v[160:163], v[184:187], v[122:125]
	v_mfma_f32_16x16x32_bf16 v[110:113], v[144:147], v[192:195], v[110:113]
	v_mfma_f32_16x16x32_bf16 v[106:109], v[160:163], v[192:195], v[106:109]
	v_mfma_f32_16x16x32_bf16 v[94:97], v[144:147], v[200:203], v[94:97]
	v_mfma_f32_16x16x32_bf16 v[90:93], v[160:163], v[200:203], v[90:93]
	v_mfma_f32_16x16x32_bf16 v[78:81], v[144:147], v[208:211], v[78:81]
	v_mfma_f32_16x16x32_bf16 v[74:77], v[160:163], v[208:211], v[74:77]
	v_mfma_f32_16x16x32_bf16 v[126:129], v[156:159], v[188:191], v[126:129]
	v_mfma_f32_16x16x32_bf16 v[122:125], v[164:167], v[188:191], v[122:125]
	v_mfma_f32_16x16x32_bf16 v[110:113], v[156:159], v[196:199], v[110:113]
	v_mfma_f32_16x16x32_bf16 v[106:109], v[164:167], v[196:199], v[106:109]
	v_mfma_f32_16x16x32_bf16 v[94:97], v[156:159], v[204:207], v[94:97]
	v_mfma_f32_16x16x32_bf16 v[90:93], v[164:167], v[204:207], v[90:93]
	v_mfma_f32_16x16x32_bf16 v[78:81], v[156:159], v[216:219], v[78:81]
	v_mfma_f32_16x16x32_bf16 v[74:77], v[164:167], v[216:219], v[74:77]
	v_mfma_f32_16x16x32_bf16 v[118:121], v[168:171], v[184:187], v[118:121]
	v_mfma_f32_16x16x32_bf16 v[114:117], v[176:179], v[184:187], v[114:117]
	v_mfma_f32_16x16x32_bf16 v[102:105], v[168:171], v[192:195], v[102:105]
	v_mfma_f32_16x16x32_bf16 v[98:101], v[176:179], v[192:195], v[98:101]
	v_mfma_f32_16x16x32_bf16 v[86:89], v[168:171], v[200:203], v[86:89]
	v_mfma_f32_16x16x32_bf16 v[82:85], v[176:179], v[200:203], v[82:85]
	v_mfma_f32_16x16x32_bf16 v[70:73], v[168:171], v[208:211], v[70:73]
	v_mfma_f32_16x16x32_bf16 v[66:69], v[176:179], v[208:211], v[66:69]
	v_mfma_f32_16x16x32_bf16 v[118:121], v[172:175], v[188:191], v[118:121]
	v_mfma_f32_16x16x32_bf16 v[114:117], v[180:183], v[188:191], v[114:117]
	v_mfma_f32_16x16x32_bf16 v[102:105], v[172:175], v[196:199], v[102:105]
	v_mfma_f32_16x16x32_bf16 v[98:101], v[180:183], v[196:199], v[98:101]
	v_mfma_f32_16x16x32_bf16 v[86:89], v[172:175], v[204:207], v[86:89]
	v_mfma_f32_16x16x32_bf16 v[82:85], v[180:183], v[204:207], v[82:85]
	v_mfma_f32_16x16x32_bf16 v[70:73], v[172:175], v[216:219], v[70:73]
	v_mfma_f32_16x16x32_bf16 v[66:69], v[180:183], v[216:219], v[66:69]
	s_barrier
	s_add_i32 s56, s56, s40
	v_lshl_add_u64 v[148:149], s[26:27], 0, v[130:131]
	s_mov_b32 m0, s56
	ds_read_b128 v[184:187], v154 offset:16384
	ds_read_b128 v[188:191], v154 offset:17408
	ds_read_b128 v[192:195], v154 offset:18432
	ds_read_b128 v[196:199], v154 offset:19456
	ds_read_b128 v[200:203], v154 offset:20480
	ds_read_b128 v[204:207], v154 offset:21504
	ds_read_b128 v[208:211], v154 offset:22528
	ds_read_b128 v[216:219], v154 offset:23552
	global_load_lds_dwordx4 v[148:149], off
	s_add_i32 m0, s56, 0x2000
	s_add_u32 s56, s26, 0x100000
	v_lshl_add_u64 v[212:213], s[26:27], 0, v[132:133]
	s_addc_u32 s57, s27, 0
	s_add_i32 s58, s58, s40
	global_load_lds_dwordx4 v[212:213], off
	v_lshl_add_u64 v[220:221], s[56:57], 0, v[130:131]
	s_mov_b32 m0, s58
	v_lshl_add_u64 v[222:223], s[28:29], 0, v[134:135]
	global_load_lds_dwordx4 v[220:221], off
	v_lshl_add_u64 v[220:221], s[56:57], 0, v[132:133]
	s_add_i32 m0, s58, 0x2000
	s_nop 0
	global_load_lds_dwordx4 v[220:221], off
	v_lshl_add_u64 v[220:221], s[28:29], 0, v[136:137]
	s_mov_b32 m0, s41
	s_nop 0
	global_load_lds_dwordx4 v[220:221], off
	s_mov_b32 m0, s44
	s_nop 0
	global_load_lds_dwordx4 v[222:223], off
	s_waitcnt vmcnt(8)
	s_waitcnt lgkmcnt(0)
	s_barrier
	s_waitcnt lgkmcnt(0)
	v_mfma_f32_16x16x32_bf16 v[62:65], v[144:147], v[184:187], v[62:65]
	v_mfma_f32_16x16x32_bf16 v[58:61], v[160:163], v[184:187], v[58:61]
	v_mfma_f32_16x16x32_bf16 v[46:49], v[144:147], v[192:195], v[46:49]
	v_mfma_f32_16x16x32_bf16 v[42:45], v[160:163], v[192:195], v[42:45]
	v_mfma_f32_16x16x32_bf16 v[30:33], v[144:147], v[200:203], v[30:33]
	v_mfma_f32_16x16x32_bf16 v[26:29], v[160:163], v[200:203], v[26:29]
	v_mfma_f32_16x16x32_bf16 v[14:17], v[144:147], v[208:211], v[14:17]
	v_mfma_f32_16x16x32_bf16 v[10:13], v[160:163], v[208:211], v[10:13]
	v_mfma_f32_16x16x32_bf16 v[62:65], v[156:159], v[188:191], v[62:65]
	v_mfma_f32_16x16x32_bf16 v[58:61], v[164:167], v[188:191], v[58:61]
	v_mfma_f32_16x16x32_bf16 v[46:49], v[156:159], v[196:199], v[46:49]
	v_mfma_f32_16x16x32_bf16 v[42:45], v[164:167], v[196:199], v[42:45]
	v_mfma_f32_16x16x32_bf16 v[30:33], v[156:159], v[204:207], v[30:33]
	v_mfma_f32_16x16x32_bf16 v[26:29], v[164:167], v[204:207], v[26:29]
	v_mfma_f32_16x16x32_bf16 v[14:17], v[156:159], v[216:219], v[14:17]
	v_mfma_f32_16x16x32_bf16 v[10:13], v[164:167], v[216:219], v[10:13]
	v_mfma_f32_16x16x32_bf16 v[54:57], v[168:171], v[184:187], v[54:57]
	v_mfma_f32_16x16x32_bf16 v[50:53], v[176:179], v[184:187], v[50:53]
	v_mfma_f32_16x16x32_bf16 v[38:41], v[168:171], v[192:195], v[38:41]
	v_mfma_f32_16x16x32_bf16 v[34:37], v[176:179], v[192:195], v[34:37]
	v_mfma_f32_16x16x32_bf16 v[22:25], v[168:171], v[200:203], v[22:25]
	v_mfma_f32_16x16x32_bf16 v[18:21], v[176:179], v[200:203], v[18:21]
	v_mfma_f32_16x16x32_bf16 v[6:9], v[168:171], v[208:211], v[6:9]
	v_mfma_f32_16x16x32_bf16 v[2:5], v[176:179], v[208:211], v[2:5]
	v_mfma_f32_16x16x32_bf16 v[54:57], v[172:175], v[188:191], v[54:57]
	v_mfma_f32_16x16x32_bf16 v[50:53], v[180:183], v[188:191], v[50:53]
	v_mfma_f32_16x16x32_bf16 v[38:41], v[172:175], v[196:199], v[38:41]
	v_mfma_f32_16x16x32_bf16 v[34:37], v[180:183], v[196:199], v[34:37]
	v_mfma_f32_16x16x32_bf16 v[22:25], v[172:175], v[204:207], v[22:25]
	v_mfma_f32_16x16x32_bf16 v[18:21], v[180:183], v[204:207], v[18:21]
	v_mfma_f32_16x16x32_bf16 v[6:9], v[172:175], v[216:219], v[6:9]
	v_mfma_f32_16x16x32_bf16 v[2:5], v[180:183], v[216:219], v[2:5]
	s_barrier
	s_add_i32 s56, 0, 0x18000
	v_add_u32_e32 v155, s56, v152
	s_add_i32 s57, 0, 0x1c000
	ds_read_b128 v[144:147], v155
	ds_read_b128 v[156:159], v155 offset:1024
	ds_read_b128 v[160:163], v155 offset:2048
	ds_read_b128 v[164:167], v155 offset:3072
	v_add_u32_e32 v155, s57, v152
	ds_read_b128 v[168:171], v155
	ds_read_b128 v[172:175], v155 offset:1024
	ds_read_b128 v[176:179], v155 offset:2048
	ds_read_b128 v[180:183], v155 offset:3072
	s_add_u32 s28, s28, 0x100000
	s_addc_u32 s29, s29, 0
	s_mov_b32 m0, s45
	v_lshl_add_u64 v[224:225], s[28:29], 0, v[136:137]
	ds_read_b128 v[184:187], v154 offset:32768
	ds_read_b128 v[188:191], v154 offset:33792
	ds_read_b128 v[192:195], v154 offset:34816
	ds_read_b128 v[196:199], v154 offset:35840
	ds_read_b128 v[200:203], v154 offset:36864
	ds_read_b128 v[204:207], v154 offset:37888
	ds_read_b128 v[208:211], v154 offset:38912
	ds_read_b128 v[216:219], v154 offset:39936
	global_load_lds_dwordx4 v[224:225], off
	v_lshl_add_u64 v[224:225], s[28:29], 0, v[134:135]
	s_mov_b32 m0, s46
	s_nop 0
	global_load_lds_dwordx4 v[224:225], off
	s_waitcnt vmcnt(8)
	s_waitcnt lgkmcnt(0)
	s_barrier
	s_waitcnt lgkmcnt(0)
	v_mfma_f32_16x16x32_bf16 v[126:129], v[144:147], v[184:187], v[126:129]
	v_mfma_f32_16x16x32_bf16 v[122:125], v[160:163], v[184:187], v[122:125]
	v_mfma_f32_16x16x32_bf16 v[110:113], v[144:147], v[192:195], v[110:113]
	v_mfma_f32_16x16x32_bf16 v[106:109], v[160:163], v[192:195], v[106:109]
	v_mfma_f32_16x16x32_bf16 v[94:97], v[144:147], v[200:203], v[94:97]
	v_mfma_f32_16x16x32_bf16 v[90:93], v[160:163], v[200:203], v[90:93]
	v_mfma_f32_16x16x32_bf16 v[78:81], v[144:147], v[208:211], v[78:81]
	v_mfma_f32_16x16x32_bf16 v[74:77], v[160:163], v[208:211], v[74:77]
	v_mfma_f32_16x16x32_bf16 v[126:129], v[156:159], v[188:191], v[126:129]
	v_mfma_f32_16x16x32_bf16 v[122:125], v[164:167], v[188:191], v[122:125]
	v_mfma_f32_16x16x32_bf16 v[110:113], v[156:159], v[196:199], v[110:113]
	v_mfma_f32_16x16x32_bf16 v[106:109], v[164:167], v[196:199], v[106:109]
	v_mfma_f32_16x16x32_bf16 v[94:97], v[156:159], v[204:207], v[94:97]
	v_mfma_f32_16x16x32_bf16 v[90:93], v[164:167], v[204:207], v[90:93]
	v_mfma_f32_16x16x32_bf16 v[78:81], v[156:159], v[216:219], v[78:81]
	v_mfma_f32_16x16x32_bf16 v[74:77], v[164:167], v[216:219], v[74:77]
	v_mfma_f32_16x16x32_bf16 v[118:121], v[168:171], v[184:187], v[118:121]
	v_mfma_f32_16x16x32_bf16 v[114:117], v[176:179], v[184:187], v[114:117]
	v_mfma_f32_16x16x32_bf16 v[102:105], v[168:171], v[192:195], v[102:105]
	v_mfma_f32_16x16x32_bf16 v[98:101], v[176:179], v[192:195], v[98:101]
	v_mfma_f32_16x16x32_bf16 v[86:89], v[168:171], v[200:203], v[86:89]
	v_mfma_f32_16x16x32_bf16 v[82:85], v[176:179], v[200:203], v[82:85]
	v_mfma_f32_16x16x32_bf16 v[70:73], v[168:171], v[208:211], v[70:73]
	v_mfma_f32_16x16x32_bf16 v[66:69], v[176:179], v[208:211], v[66:69]
	v_mfma_f32_16x16x32_bf16 v[118:121], v[172:175], v[188:191], v[118:121]
	v_mfma_f32_16x16x32_bf16 v[114:117], v[180:183], v[188:191], v[114:117]
	v_mfma_f32_16x16x32_bf16 v[102:105], v[172:175], v[196:199], v[102:105]
	v_mfma_f32_16x16x32_bf16 v[98:101], v[180:183], v[196:199], v[98:101]
	v_mfma_f32_16x16x32_bf16 v[86:89], v[172:175], v[204:207], v[86:89]
	v_mfma_f32_16x16x32_bf16 v[82:85], v[180:183], v[204:207], v[82:85]
	v_mfma_f32_16x16x32_bf16 v[70:73], v[172:175], v[216:219], v[70:73]
	v_mfma_f32_16x16x32_bf16 v[66:69], v[180:183], v[216:219], v[66:69]
	s_barrier
	s_add_i32 s28, s56, s40
	v_lshl_add_u64 v[148:149], v[148:149], 0, s[18:19]
	s_mov_b32 m0, s28
	ds_read_b128 v[184:187], v154 offset:49152
	ds_read_b128 v[188:191], v154 offset:50176
	ds_read_b128 v[192:195], v154 offset:51200
	ds_read_b128 v[196:199], v154 offset:52224
	ds_read_b128 v[200:203], v154 offset:53248
	ds_read_b128 v[204:207], v154 offset:54272
	ds_read_b128 v[208:211], v154 offset:55296
	ds_read_b128 v[216:219], v154 offset:56320
	global_load_lds_dwordx4 v[148:149], off
	s_add_i32 m0, s28, 0x2000
	s_add_u32 s26, s26, 0x100080
	v_lshl_add_u64 v[148:149], v[212:213], 0, s[18:19]
	s_addc_u32 s27, s27, 0
	s_add_i32 s28, s57, s40
	global_load_lds_dwordx4 v[148:149], off
	v_lshl_add_u64 v[148:149], s[26:27], 0, v[130:131]
	s_mov_b32 m0, s28
	s_nop 0
	global_load_lds_dwordx4 v[148:149], off
	v_lshl_add_u64 v[148:149], s[26:27], 0, v[132:133]
	s_add_i32 m0, s28, 0x2000
	s_nop 0
	global_load_lds_dwordx4 v[148:149], off
	v_lshl_add_u64 v[148:149], v[220:221], 0, s[18:19]
	s_mov_b32 m0, s30
	s_nop 0
	global_load_lds_dwordx4 v[148:149], off
	v_lshl_add_u64 v[148:149], v[222:223], 0, s[18:19]
	s_mov_b32 m0, s47
	s_nop 0
	global_load_lds_dwordx4 v[148:149], off
	s_waitcnt vmcnt(8)
	s_waitcnt lgkmcnt(0)
	s_barrier
	s_waitcnt lgkmcnt(0)
	v_mfma_f32_16x16x32_bf16 v[62:65], v[144:147], v[184:187], v[62:65]
	v_mfma_f32_16x16x32_bf16 v[58:61], v[160:163], v[184:187], v[58:61]
	v_mfma_f32_16x16x32_bf16 v[46:49], v[144:147], v[192:195], v[46:49]
	v_mfma_f32_16x16x32_bf16 v[42:45], v[160:163], v[192:195], v[42:45]
	v_mfma_f32_16x16x32_bf16 v[30:33], v[144:147], v[200:203], v[30:33]
	v_mfma_f32_16x16x32_bf16 v[26:29], v[160:163], v[200:203], v[26:29]
	v_mfma_f32_16x16x32_bf16 v[14:17], v[144:147], v[208:211], v[14:17]
	v_mfma_f32_16x16x32_bf16 v[10:13], v[160:163], v[208:211], v[10:13]
	v_mfma_f32_16x16x32_bf16 v[62:65], v[156:159], v[188:191], v[62:65]
	v_mfma_f32_16x16x32_bf16 v[58:61], v[164:167], v[188:191], v[58:61]
	v_mfma_f32_16x16x32_bf16 v[46:49], v[156:159], v[196:199], v[46:49]
	v_mfma_f32_16x16x32_bf16 v[42:45], v[164:167], v[196:199], v[42:45]
	v_mfma_f32_16x16x32_bf16 v[30:33], v[156:159], v[204:207], v[30:33]
	v_mfma_f32_16x16x32_bf16 v[26:29], v[164:167], v[204:207], v[26:29]
	v_mfma_f32_16x16x32_bf16 v[14:17], v[156:159], v[216:219], v[14:17]
	v_mfma_f32_16x16x32_bf16 v[10:13], v[164:167], v[216:219], v[10:13]
	v_mfma_f32_16x16x32_bf16 v[54:57], v[168:171], v[184:187], v[54:57]
	v_mfma_f32_16x16x32_bf16 v[50:53], v[176:179], v[184:187], v[50:53]
	v_mfma_f32_16x16x32_bf16 v[38:41], v[168:171], v[192:195], v[38:41]
	v_mfma_f32_16x16x32_bf16 v[34:37], v[176:179], v[192:195], v[34:37]
	v_mfma_f32_16x16x32_bf16 v[22:25], v[168:171], v[200:203], v[22:25]
	v_mfma_f32_16x16x32_bf16 v[18:21], v[176:179], v[200:203], v[18:21]
	v_mfma_f32_16x16x32_bf16 v[6:9], v[168:171], v[208:211], v[6:9]
	v_mfma_f32_16x16x32_bf16 v[2:5], v[176:179], v[208:211], v[2:5]
	v_mfma_f32_16x16x32_bf16 v[54:57], v[172:175], v[188:191], v[54:57]
	v_mfma_f32_16x16x32_bf16 v[50:53], v[180:183], v[188:191], v[50:53]
	v_mfma_f32_16x16x32_bf16 v[38:41], v[172:175], v[196:199], v[38:41]
	v_mfma_f32_16x16x32_bf16 v[34:37], v[180:183], v[196:199], v[34:37]
	v_mfma_f32_16x16x32_bf16 v[22:25], v[172:175], v[204:207], v[22:25]
	v_mfma_f32_16x16x32_bf16 v[18:21], v[180:183], v[204:207], v[18:21]
	v_mfma_f32_16x16x32_bf16 v[6:9], v[172:175], v[216:219], v[6:9]
	v_mfma_f32_16x16x32_bf16 v[2:5], v[180:183], v[216:219], v[2:5]
	s_barrier
	s_add_i32 s55, s55, 2
	s_add_u32 s24, s24, 0x100
	s_addc_u32 s25, s25, 0
	s_add_u32 s53, s53, 0x100
	s_addc_u32 s54, s54, 0
	s_cmp_gt_u32 s55, 61
	s_cbranch_scc0 .LBB0_872
	s_and_b64 vcc, exec, s[6:7]
	s_cbranch_vccz .LBB0_875
	s_barrier

.LBB0_1024:
	s_add_u32 s46, s2, 0xfff00080
	s_addc_u32 s47, s3, -1
	s_add_i32 s83, 0, 0x10000
	s_cmp_eq_u32 s82, 60
	s_cselect_b32 s59, s30, s47
	s_cselect_b32 s58, s53, s46
	s_cselect_b32 s47, s51, s81
	s_cselect_b32 s46, s79, s80
	s_add_i32 s86, 0, 0x14000
	v_add_u32_e32 v74, s83, v244
	v_add_u32_e32 v94, s86, v244
	ds_read_b128 v[62:65], v74
	ds_read_b128 v[66:69], v74 offset:1024
	ds_read_b128 v[70:73], v74 offset:2048
	ds_read_b128 v[74:77], v74 offset:3072
	ds_read_b128 v[78:81], v94
	ds_read_b128 v[82:85], v94 offset:1024
	ds_read_b128 v[90:93], v94 offset:2048
	ds_read_b128 v[94:97], v94 offset:3072
	v_lshl_add_u64 v[196:197], s[2:3], 0, v[222:223]
	s_add_i32 m0, s67, 0xc000
	ds_read_b128 v[98:101], v250
	ds_read_b128 v[102:105], v250 offset:1024
	ds_read_b128 v[106:109], v250 offset:2048
	ds_read_b128 v[110:113], v250 offset:3072
	ds_read_b128 v[180:183], v250 offset:4096
	ds_read_b128 v[184:187], v250 offset:5120
	ds_read_b128 v[188:191], v250 offset:6144
	ds_read_b128 v[192:195], v250 offset:7168
	global_load_lds_dwordx4 v[196:197], off
	v_lshl_add_u64 v[196:197], s[2:3], 0, v[224:225]
	s_add_i32 m0, s67, 0xe000
	s_nop 0
	global_load_lds_dwordx4 v[196:197], off
	s_waitcnt vmcnt(8)
	s_waitcnt lgkmcnt(0)
	s_barrier
	s_waitcnt lgkmcnt(0)
	v_mfma_f32_16x16x32_bf16 v[176:179], v[62:65], v[98:101], v[176:179]
	v_mfma_f32_16x16x32_bf16 v[168:171], v[70:73], v[98:101], v[168:171]
	v_mfma_f32_16x16x32_bf16 v[160:163], v[62:65], v[106:109], v[160:163]
	v_mfma_f32_16x16x32_bf16 v[152:155], v[70:73], v[106:109], v[152:155]
	v_mfma_f32_16x16x32_bf16 v[144:147], v[62:65], v[180:183], v[144:147]
	v_mfma_f32_16x16x32_bf16 v[136:139], v[70:73], v[180:183], v[136:139]
	v_mfma_f32_16x16x32_bf16 v[126:129], v[62:65], v[188:191], v[126:129]
	v_mfma_f32_16x16x32_bf16 v[118:121], v[70:73], v[188:191], v[118:121]
	v_mfma_f32_16x16x32_bf16 v[176:179], v[66:69], v[102:105], v[176:179]
	v_mfma_f32_16x16x32_bf16 v[168:171], v[74:77], v[102:105], v[168:171]
	v_mfma_f32_16x16x32_bf16 v[160:163], v[66:69], v[110:113], v[160:163]
	v_mfma_f32_16x16x32_bf16 v[152:155], v[74:77], v[110:113], v[152:155]
	v_mfma_f32_16x16x32_bf16 v[144:147], v[66:69], v[184:187], v[144:147]
	v_mfma_f32_16x16x32_bf16 v[136:139], v[74:77], v[184:187], v[136:139]
	v_mfma_f32_16x16x32_bf16 v[126:129], v[66:69], v[192:195], v[126:129]
	v_mfma_f32_16x16x32_bf16 v[118:121], v[74:77], v[192:195], v[118:121]
	v_mfma_f32_16x16x32_bf16 v[172:175], v[78:81], v[98:101], v[172:175]
	v_mfma_f32_16x16x32_bf16 v[98:101], v[90:93], v[98:101], v[164:167]
	v_mfma_f32_16x16x32_bf16 v[172:175], v[82:85], v[102:105], v[172:175]
	v_mfma_f32_16x16x32_bf16 v[98:101], v[94:97], v[102:105], v[98:101]
	v_mfma_f32_16x16x32_bf16 v[102:105], v[78:81], v[106:109], v[156:159]
	v_mfma_f32_16x16x32_bf16 v[106:109], v[90:93], v[106:109], v[148:151]
	v_mfma_f32_16x16x32_bf16 v[132:135], v[90:93], v[180:183], v[132:135]
	v_mfma_f32_16x16x32_bf16 v[122:125], v[78:81], v[188:191], v[122:125]
	v_mfma_f32_16x16x32_bf16 v[114:117], v[90:93], v[188:191], v[114:117]
	v_mfma_f32_16x16x32_bf16 v[102:105], v[82:85], v[110:113], v[102:105]
	v_mfma_f32_16x16x32_bf16 v[106:109], v[94:97], v[110:113], v[106:109]
	v_mfma_f32_16x16x32_bf16 v[110:113], v[78:81], v[180:183], v[140:143]
	v_mfma_f32_16x16x32_bf16 v[132:135], v[94:97], v[184:187], v[132:135]
	v_mfma_f32_16x16x32_bf16 v[122:125], v[82:85], v[192:195], v[122:125]
	v_mfma_f32_16x16x32_bf16 v[114:117], v[94:97], v[192:195], v[114:117]
	v_mfma_f32_16x16x32_bf16 v[110:113], v[82:85], v[184:187], v[110:113]
	s_barrier
	s_add_i32 s83, s83, s66
	v_lshl_add_u64 v[204:205], s[46:47], 0, v[130:131]
	s_mov_b32 m0, s83
	ds_read_b128 v[140:143], v250 offset:16384
	ds_read_b128 v[148:151], v250 offset:17408
	ds_read_b128 v[156:159], v250 offset:18432
	ds_read_b128 v[164:167], v250 offset:19456
	ds_read_b128 v[180:183], v250 offset:20480
	ds_read_b128 v[184:187], v250 offset:21504
	ds_read_b128 v[188:191], v250 offset:22528
	ds_read_b128 v[192:195], v250 offset:23552
	global_load_lds_dwordx4 v[204:205], off
	s_add_i32 m0, s83, 0x2000
	s_add_u32 s84, s46, 0x100000
	v_lshl_add_u64 v[206:207], s[46:47], 0, v[216:217]
	s_addc_u32 s85, s47, 0
	s_add_i32 s83, s86, s66
	global_load_lds_dwordx4 v[206:207], off
	v_lshl_add_u64 v[196:197], s[84:85], 0, v[130:131]
	s_mov_b32 m0, s83
	v_lshl_add_u64 v[208:209], s[58:59], 0, v[220:221]
	global_load_lds_dwordx4 v[196:197], off
	v_lshl_add_u64 v[196:197], s[84:85], 0, v[216:217]
	s_add_i32 m0, s83, 0x2000
	v_lshl_add_u64 v[210:211], s[58:59], 0, v[218:219]
	global_load_lds_dwordx4 v[196:197], off
	s_mov_b32 m0, s67
	s_nop 0
	global_load_lds_dwordx4 v[208:209], off
	s_mov_b32 m0, s68
	s_nop 0
	global_load_lds_dwordx4 v[210:211], off
	s_waitcnt vmcnt(8)
	s_waitcnt lgkmcnt(0)
	s_barrier
	s_waitcnt lgkmcnt(0)
	v_mfma_f32_16x16x32_bf16 v[86:89], v[62:65], v[140:143], v[86:89]
	v_mfma_f32_16x16x32_bf16 v[54:57], v[70:73], v[140:143], v[54:57]
	v_mfma_f32_16x16x32_bf16 v[46:49], v[62:65], v[156:159], v[46:49]
	v_mfma_f32_16x16x32_bf16 v[38:41], v[70:73], v[156:159], v[38:41]
	v_mfma_f32_16x16x32_bf16 v[30:33], v[62:65], v[180:183], v[30:33]
	v_mfma_f32_16x16x32_bf16 v[22:25], v[70:73], v[180:183], v[22:25]
	v_mfma_f32_16x16x32_bf16 v[14:17], v[62:65], v[188:191], v[14:17]
	v_mfma_f32_16x16x32_bf16 v[6:9], v[70:73], v[188:191], v[6:9]
	v_mfma_f32_16x16x32_bf16 v[86:89], v[66:69], v[148:151], v[86:89]
	v_mfma_f32_16x16x32_bf16 v[54:57], v[74:77], v[148:151], v[54:57]
	v_mfma_f32_16x16x32_bf16 v[46:49], v[66:69], v[164:167], v[46:49]
	v_mfma_f32_16x16x32_bf16 v[38:41], v[74:77], v[164:167], v[38:41]
	v_mfma_f32_16x16x32_bf16 v[30:33], v[66:69], v[184:187], v[30:33]
	v_mfma_f32_16x16x32_bf16 v[22:25], v[74:77], v[184:187], v[22:25]
	v_mfma_f32_16x16x32_bf16 v[14:17], v[66:69], v[192:195], v[14:17]
	v_mfma_f32_16x16x32_bf16 v[6:9], v[74:77], v[192:195], v[6:9]
	v_mfma_f32_16x16x32_bf16 v[58:61], v[78:81], v[140:143], v[58:61]
	v_mfma_f32_16x16x32_bf16 v[50:53], v[90:93], v[140:143], v[50:53]
	v_mfma_f32_16x16x32_bf16 v[42:45], v[78:81], v[156:159], v[42:45]
	v_mfma_f32_16x16x32_bf16 v[34:37], v[90:93], v[156:159], v[34:37]
	v_mfma_f32_16x16x32_bf16 v[26:29], v[78:81], v[180:183], v[26:29]
	v_mfma_f32_16x16x32_bf16 v[18:21], v[90:93], v[180:183], v[18:21]
	v_mfma_f32_16x16x32_bf16 v[10:13], v[78:81], v[188:191], v[10:13]
	v_mfma_f32_16x16x32_bf16 v[2:5], v[90:93], v[188:191], v[2:5]
	v_mfma_f32_16x16x32_bf16 v[58:61], v[82:85], v[148:151], v[58:61]
	v_mfma_f32_16x16x32_bf16 v[50:53], v[94:97], v[148:151], v[50:53]
	v_mfma_f32_16x16x32_bf16 v[42:45], v[82:85], v[164:167], v[42:45]
	v_mfma_f32_16x16x32_bf16 v[34:37], v[94:97], v[164:167], v[34:37]
	v_mfma_f32_16x16x32_bf16 v[26:29], v[82:85], v[184:187], v[26:29]
	v_mfma_f32_16x16x32_bf16 v[18:21], v[94:97], v[184:187], v[18:21]
	v_mfma_f32_16x16x32_bf16 v[10:13], v[82:85], v[192:195], v[10:13]
	v_mfma_f32_16x16x32_bf16 v[2:5], v[94:97], v[192:195], v[2:5]
	s_barrier
	s_add_i32 s83, 0, 0x18000
	s_add_i32 s84, 0, 0x1c000
	v_add_u32_e32 v74, s83, v244
	v_add_u32_e32 v94, s84, v244
	ds_read_b128 v[62:65], v74
	ds_read_b128 v[66:69], v74 offset:1024
	ds_read_b128 v[70:73], v74 offset:2048
	ds_read_b128 v[74:77], v74 offset:3072
	ds_read_b128 v[78:81], v94
	ds_read_b128 v[82:85], v94 offset:1024
	ds_read_b128 v[90:93], v94 offset:2048
	ds_read_b128 v[94:97], v94 offset:3072
	s_add_u32 s58, s58, 0x100000
	s_addc_u32 s59, s59, 0
	s_mov_b32 m0, s69
	v_lshl_add_u64 v[156:157], s[58:59], 0, v[220:221]
	ds_read_b128 v[140:143], v250 offset:32768
	ds_read_b128 v[148:151], v250 offset:33792
	ds_read_b128 v[180:183], v250 offset:34816
	ds_read_b128 v[184:187], v250 offset:35840
	ds_read_b128 v[188:191], v250 offset:36864
	ds_read_b128 v[192:195], v250 offset:37888
	ds_read_b128 v[196:199], v250 offset:38912
	ds_read_b128 v[200:203], v250 offset:39936
	global_load_lds_dwordx4 v[156:157], off
	v_lshl_add_u64 v[156:157], s[58:59], 0, v[218:219]
	s_mov_b32 m0, s70
	s_nop 0
	global_load_lds_dwordx4 v[156:157], off
	s_waitcnt vmcnt(8)
	s_waitcnt lgkmcnt(0)
	s_barrier
	s_waitcnt lgkmcnt(0)
	v_mfma_f32_16x16x32_bf16 v[156:159], v[62:65], v[140:143], v[176:179]
	v_mfma_f32_16x16x32_bf16 v[176:179], v[66:69], v[148:151], v[156:159]
	v_mfma_f32_16x16x32_bf16 v[156:159], v[70:73], v[140:143], v[168:171]
	v_mfma_f32_16x16x32_bf16 v[168:171], v[74:77], v[148:151], v[156:159]
	v_mfma_f32_16x16x32_bf16 v[156:159], v[62:65], v[180:183], v[160:163]
	v_mfma_f32_16x16x32_bf16 v[152:155], v[70:73], v[180:183], v[152:155]
	v_mfma_f32_16x16x32_bf16 v[144:147], v[62:65], v[188:191], v[144:147]
	v_mfma_f32_16x16x32_bf16 v[136:139], v[70:73], v[188:191], v[136:139]
	v_mfma_f32_16x16x32_bf16 v[126:129], v[62:65], v[196:199], v[126:129]
	v_mfma_f32_16x16x32_bf16 v[118:121], v[70:73], v[196:199], v[118:121]
	v_mfma_f32_16x16x32_bf16 v[160:163], v[66:69], v[184:187], v[156:159]
	v_mfma_f32_16x16x32_bf16 v[152:155], v[74:77], v[184:187], v[152:155]
	v_mfma_f32_16x16x32_bf16 v[144:147], v[66:69], v[192:195], v[144:147]
	v_mfma_f32_16x16x32_bf16 v[136:139], v[74:77], v[192:195], v[136:139]
	v_mfma_f32_16x16x32_bf16 v[126:129], v[66:69], v[200:203], v[126:129]
	v_mfma_f32_16x16x32_bf16 v[118:121], v[74:77], v[200:203], v[118:121]
	v_mfma_f32_16x16x32_bf16 v[98:101], v[90:93], v[140:143], v[98:101]
	v_mfma_f32_16x16x32_bf16 v[156:159], v[78:81], v[140:143], v[172:175]
	v_mfma_f32_16x16x32_bf16 v[164:167], v[94:97], v[148:151], v[98:101]
	v_mfma_f32_16x16x32_bf16 v[98:101], v[78:81], v[180:183], v[102:105]
	v_mfma_f32_16x16x32_bf16 v[172:175], v[82:85], v[148:151], v[156:159]
	v_mfma_f32_16x16x32_bf16 v[156:159], v[82:85], v[184:187], v[98:101]
	v_mfma_f32_16x16x32_bf16 v[98:101], v[90:93], v[180:183], v[106:109]
	v_mfma_f32_16x16x32_bf16 v[148:151], v[94:97], v[184:187], v[98:101]
	v_mfma_f32_16x16x32_bf16 v[98:101], v[78:81], v[188:191], v[110:113]
	v_mfma_f32_16x16x32_bf16 v[140:143], v[82:85], v[192:195], v[98:101]
	v_mfma_f32_16x16x32_bf16 v[98:101], v[90:93], v[188:191], v[132:135]
	v_mfma_f32_16x16x32_bf16 v[132:135], v[94:97], v[192:195], v[98:101]
	v_mfma_f32_16x16x32_bf16 v[98:101], v[78:81], v[196:199], v[122:125]
	v_mfma_f32_16x16x32_bf16 v[122:125], v[82:85], v[200:203], v[98:101]
	v_mfma_f32_16x16x32_bf16 v[98:101], v[90:93], v[196:199], v[114:117]
	v_mfma_f32_16x16x32_bf16 v[114:117], v[94:97], v[200:203], v[98:101]
	s_barrier
	s_add_i32 s58, s83, s66
	v_lshl_add_u64 v[196:197], v[204:205], 0, s[18:19]
	s_mov_b32 m0, s58
	s_nop 1
	ds_read_b128 v[98:101], v250 offset:49152
	ds_read_b128 v[102:105], v250 offset:50176
	ds_read_b128 v[106:109], v250 offset:51200
	ds_read_b128 v[110:113], v250 offset:52224
	ds_read_b128 v[180:183], v250 offset:53248
	ds_read_b128 v[184:187], v250 offset:54272
	ds_read_b128 v[188:191], v250 offset:55296
	ds_read_b128 v[192:195], v250 offset:56320
	global_load_lds_dwordx4 v[196:197], off
	s_add_i32 m0, s58, 0x2000
	s_add_u32 s46, s46, 0x100080
	v_lshl_add_u64 v[196:197], v[206:207], 0, s[18:19]
	s_addc_u32 s47, s47, 0
	s_add_i32 s58, s84, s66
	global_load_lds_dwordx4 v[196:197], off
	v_lshl_add_u64 v[196:197], s[46:47], 0, v[130:131]
	s_mov_b32 m0, s58
	s_nop 0
	global_load_lds_dwordx4 v[196:197], off
	v_lshl_add_u64 v[196:197], s[46:47], 0, v[216:217]
	s_add_i32 m0, s58, 0x2000
	s_nop 0
	global_load_lds_dwordx4 v[196:197], off
	v_lshl_add_u64 v[196:197], v[208:209], 0, s[18:19]
	s_mov_b32 m0, s74
	s_nop 0
	global_load_lds_dwordx4 v[196:197], off
	v_lshl_add_u64 v[196:197], v[210:211], 0, s[18:19]
	s_mov_b32 m0, s75
	s_nop 0
	global_load_lds_dwordx4 v[196:197], off
	s_waitcnt vmcnt(8)
	s_waitcnt lgkmcnt(0)
	s_barrier
	s_waitcnt lgkmcnt(0)
	v_mfma_f32_16x16x32_bf16 v[86:89], v[62:65], v[98:101], v[86:89]
	v_mfma_f32_16x16x32_bf16 v[54:57], v[70:73], v[98:101], v[54:57]
	v_mfma_f32_16x16x32_bf16 v[46:49], v[62:65], v[106:109], v[46:49]
	v_mfma_f32_16x16x32_bf16 v[38:41], v[70:73], v[106:109], v[38:41]
	v_mfma_f32_16x16x32_bf16 v[30:33], v[62:65], v[180:183], v[30:33]
	v_mfma_f32_16x16x32_bf16 v[22:25], v[70:73], v[180:183], v[22:25]
	v_mfma_f32_16x16x32_bf16 v[14:17], v[62:65], v[188:191], v[14:17]
	v_mfma_f32_16x16x32_bf16 v[6:9], v[70:73], v[188:191], v[6:9]
	v_mfma_f32_16x16x32_bf16 v[86:89], v[66:69], v[102:105], v[86:89]
	v_mfma_f32_16x16x32_bf16 v[54:57], v[74:77], v[102:105], v[54:57]
	v_mfma_f32_16x16x32_bf16 v[46:49], v[66:69], v[110:113], v[46:49]
	v_mfma_f32_16x16x32_bf16 v[38:41], v[74:77], v[110:113], v[38:41]
	v_mfma_f32_16x16x32_bf16 v[30:33], v[66:69], v[184:187], v[30:33]
	v_mfma_f32_16x16x32_bf16 v[22:25], v[74:77], v[184:187], v[22:25]
	v_mfma_f32_16x16x32_bf16 v[14:17], v[66:69], v[192:195], v[14:17]
	v_mfma_f32_16x16x32_bf16 v[6:9], v[74:77], v[192:195], v[6:9]
	v_mfma_f32_16x16x32_bf16 v[58:61], v[78:81], v[98:101], v[58:61]
	v_mfma_f32_16x16x32_bf16 v[50:53], v[90:93], v[98:101], v[50:53]
	v_mfma_f32_16x16x32_bf16 v[42:45], v[78:81], v[106:109], v[42:45]
	v_mfma_f32_16x16x32_bf16 v[34:37], v[90:93], v[106:109], v[34:37]
	v_mfma_f32_16x16x32_bf16 v[26:29], v[78:81], v[180:183], v[26:29]
	v_mfma_f32_16x16x32_bf16 v[18:21], v[90:93], v[180:183], v[18:21]
	v_mfma_f32_16x16x32_bf16 v[10:13], v[78:81], v[188:191], v[10:13]
	v_mfma_f32_16x16x32_bf16 v[2:5], v[90:93], v[188:191], v[2:5]
	v_mfma_f32_16x16x32_bf16 v[58:61], v[82:85], v[102:105], v[58:61]
	v_mfma_f32_16x16x32_bf16 v[50:53], v[94:97], v[102:105], v[50:53]
	v_mfma_f32_16x16x32_bf16 v[42:45], v[82:85], v[110:113], v[42:45]
	v_mfma_f32_16x16x32_bf16 v[34:37], v[94:97], v[110:113], v[34:37]
	v_mfma_f32_16x16x32_bf16 v[26:29], v[82:85], v[184:187], v[26:29]
	v_mfma_f32_16x16x32_bf16 v[18:21], v[94:97], v[184:187], v[18:21]
	v_mfma_f32_16x16x32_bf16 v[10:13], v[82:85], v[192:195], v[10:13]
	v_mfma_f32_16x16x32_bf16 v[2:5], v[94:97], v[192:195], v[2:5]
	s_barrier
	s_add_i32 s82, s82, 2
	s_add_u32 s2, s2, 0x100
	s_addc_u32 s3, s3, 0
	s_add_u32 s80, s80, 0x100
	s_addc_u32 s81, s81, 0
	s_cmp_gt_u32 s82, 61
	s_cbranch_scc0 .LBB0_1024
	v_mov_b64_e32 v[214:215], 0x400
	s_and_b64 vcc, exec, s[16:17]
	s_cbranch_vccz .LBB0_1027
	s_barrier

.LBB0_1328:
	s_add_u32 s24, s22, 0x100
	s_addc_u32 s25, s23, 0
	s_add_i32 s57, 0, 0x10000
	s_cmpk_eq_i32 s56, 0xa8
	s_cselect_b32 s29, s3, s25
	s_cselect_b32 s28, s2, s24
	v_add_u32_e32 v146, s57, v149
	s_cselect_b32 s27, s17, s55
	s_cselect_b32 s26, s16, s54
	s_add_i32 s58, 0, 0x14000
	ds_read_b128 v[142:145], v146
	ds_read_b128 v[152:155], v146 offset:1024
	ds_read_b128 v[156:159], v146 offset:2048
	ds_read_b128 v[160:163], v146 offset:3072
	v_add_u32_e32 v146, s58, v149
	ds_read_b128 v[164:167], v146
	ds_read_b128 v[168:171], v146 offset:1024
	ds_read_b128 v[172:175], v146 offset:2048
	ds_read_b128 v[176:179], v146 offset:3072
	v_lshl_add_u64 v[146:147], s[22:23], 0, v[138:139]
	s_add_i32 m0, s41, 0xc000
	ds_read_b128 v[180:183], v151
	ds_read_b128 v[184:187], v151 offset:1024
	ds_read_b128 v[188:191], v151 offset:2048
	ds_read_b128 v[192:195], v151 offset:3072
	ds_read_b128 v[196:199], v151 offset:4096
	ds_read_b128 v[200:203], v151 offset:5120
	ds_read_b128 v[204:207], v151 offset:6144
	ds_read_b128 v[208:211], v151 offset:7168
	global_load_lds_dwordx4 v[146:147], off
	v_lshl_add_u64 v[146:147], s[22:23], 0, v[140:141]
	s_add_i32 m0, s41, 0xe000
	s_nop 0
	global_load_lds_dwordx4 v[146:147], off
	s_waitcnt vmcnt(8)
	s_waitcnt lgkmcnt(0)
	s_barrier
	s_waitcnt lgkmcnt(0)
	v_mfma_f32_16x16x32_bf16 v[126:129], v[142:145], v[180:183], v[126:129]
	v_mfma_f32_16x16x32_bf16 v[122:125], v[156:159], v[180:183], v[122:125]
	v_mfma_f32_16x16x32_bf16 v[110:113], v[142:145], v[188:191], v[110:113]
	v_mfma_f32_16x16x32_bf16 v[106:109], v[156:159], v[188:191], v[106:109]
	v_mfma_f32_16x16x32_bf16 v[94:97], v[142:145], v[196:199], v[94:97]
	v_mfma_f32_16x16x32_bf16 v[90:93], v[156:159], v[196:199], v[90:93]
	v_mfma_f32_16x16x32_bf16 v[78:81], v[142:145], v[204:207], v[78:81]
	v_mfma_f32_16x16x32_bf16 v[74:77], v[156:159], v[204:207], v[74:77]
	v_mfma_f32_16x16x32_bf16 v[126:129], v[152:155], v[184:187], v[126:129]
	v_mfma_f32_16x16x32_bf16 v[122:125], v[160:163], v[184:187], v[122:125]
	v_mfma_f32_16x16x32_bf16 v[110:113], v[152:155], v[192:195], v[110:113]
	v_mfma_f32_16x16x32_bf16 v[106:109], v[160:163], v[192:195], v[106:109]
	v_mfma_f32_16x16x32_bf16 v[94:97], v[152:155], v[200:203], v[94:97]
	v_mfma_f32_16x16x32_bf16 v[90:93], v[160:163], v[200:203], v[90:93]
	v_mfma_f32_16x16x32_bf16 v[78:81], v[152:155], v[208:211], v[78:81]
	v_mfma_f32_16x16x32_bf16 v[74:77], v[160:163], v[208:211], v[74:77]
	v_mfma_f32_16x16x32_bf16 v[118:121], v[164:167], v[180:183], v[118:121]
	v_mfma_f32_16x16x32_bf16 v[114:117], v[172:175], v[180:183], v[114:117]
	v_mfma_f32_16x16x32_bf16 v[102:105], v[164:167], v[188:191], v[102:105]
	v_mfma_f32_16x16x32_bf16 v[98:101], v[172:175], v[188:191], v[98:101]
	v_mfma_f32_16x16x32_bf16 v[86:89], v[164:167], v[196:199], v[86:89]
	v_mfma_f32_16x16x32_bf16 v[82:85], v[172:175], v[196:199], v[82:85]
	v_mfma_f32_16x16x32_bf16 v[70:73], v[164:167], v[204:207], v[70:73]
	v_mfma_f32_16x16x32_bf16 v[66:69], v[172:175], v[204:207], v[66:69]
	v_mfma_f32_16x16x32_bf16 v[118:121], v[168:171], v[184:187], v[118:121]
	v_mfma_f32_16x16x32_bf16 v[114:117], v[176:179], v[184:187], v[114:117]
	v_mfma_f32_16x16x32_bf16 v[102:105], v[168:171], v[192:195], v[102:105]
	v_mfma_f32_16x16x32_bf16 v[98:101], v[176:179], v[192:195], v[98:101]
	v_mfma_f32_16x16x32_bf16 v[86:89], v[168:171], v[200:203], v[86:89]
	v_mfma_f32_16x16x32_bf16 v[82:85], v[176:179], v[200:203], v[82:85]
	v_mfma_f32_16x16x32_bf16 v[70:73], v[168:171], v[208:211], v[70:73]
	v_mfma_f32_16x16x32_bf16 v[66:69], v[176:179], v[208:211], v[66:69]
	s_barrier
	s_add_i32 s22, s57, s40
	v_lshl_add_u64 v[146:147], s[26:27], 0, v[130:131]
	s_mov_b32 m0, s22
	ds_read_b128 v[180:183], v151 offset:16384
	ds_read_b128 v[184:187], v151 offset:17408
	ds_read_b128 v[188:191], v151 offset:18432
	ds_read_b128 v[192:195], v151 offset:19456
	ds_read_b128 v[196:199], v151 offset:20480
	ds_read_b128 v[200:203], v151 offset:21504
	ds_read_b128 v[204:207], v151 offset:22528
	ds_read_b128 v[208:211], v151 offset:23552
	global_load_lds_dwordx4 v[146:147], off
	s_add_i32 m0, s22, 0x2000
	s_add_u32 s22, s26, 0x2b0000
	v_lshl_add_u64 v[212:213], s[26:27], 0, v[132:133]
	s_addc_u32 s23, s27, 0
	s_add_i32 s57, s58, s40
	global_load_lds_dwordx4 v[212:213], off
	v_lshl_add_u64 v[216:217], s[22:23], 0, v[130:131]
	s_mov_b32 m0, s57
	v_lshl_add_u64 v[218:219], s[28:29], 0, v[134:135]
	global_load_lds_dwordx4 v[216:217], off
	v_lshl_add_u64 v[216:217], s[22:23], 0, v[132:133]
	s_add_i32 m0, s57, 0x2000
	s_nop 0
	global_load_lds_dwordx4 v[216:217], off
	v_lshl_add_u64 v[216:217], s[28:29], 0, v[136:137]
	s_mov_b32 m0, s41
	s_nop 0
	global_load_lds_dwordx4 v[216:217], off
	s_mov_b32 m0, s44
	s_nop 0
	global_load_lds_dwordx4 v[218:219], off
	s_waitcnt vmcnt(8)
	s_waitcnt lgkmcnt(0)
	s_barrier
	s_waitcnt lgkmcnt(0)
	v_mfma_f32_16x16x32_bf16 v[62:65], v[142:145], v[180:183], v[62:65]
	v_mfma_f32_16x16x32_bf16 v[58:61], v[156:159], v[180:183], v[58:61]
	v_mfma_f32_16x16x32_bf16 v[46:49], v[142:145], v[188:191], v[46:49]
	v_mfma_f32_16x16x32_bf16 v[42:45], v[156:159], v[188:191], v[42:45]
	v_mfma_f32_16x16x32_bf16 v[30:33], v[142:145], v[196:199], v[30:33]
	v_mfma_f32_16x16x32_bf16 v[26:29], v[156:159], v[196:199], v[26:29]
	v_mfma_f32_16x16x32_bf16 v[14:17], v[142:145], v[204:207], v[14:17]
	v_mfma_f32_16x16x32_bf16 v[10:13], v[156:159], v[204:207], v[10:13]
	v_mfma_f32_16x16x32_bf16 v[62:65], v[152:155], v[184:187], v[62:65]
	v_mfma_f32_16x16x32_bf16 v[58:61], v[160:163], v[184:187], v[58:61]
	v_mfma_f32_16x16x32_bf16 v[46:49], v[152:155], v[192:195], v[46:49]
	v_mfma_f32_16x16x32_bf16 v[42:45], v[160:163], v[192:195], v[42:45]
	v_mfma_f32_16x16x32_bf16 v[30:33], v[152:155], v[200:203], v[30:33]
	v_mfma_f32_16x16x32_bf16 v[26:29], v[160:163], v[200:203], v[26:29]
	v_mfma_f32_16x16x32_bf16 v[14:17], v[152:155], v[208:211], v[14:17]
	v_mfma_f32_16x16x32_bf16 v[10:13], v[160:163], v[208:211], v[10:13]
	v_mfma_f32_16x16x32_bf16 v[54:57], v[164:167], v[180:183], v[54:57]
	v_mfma_f32_16x16x32_bf16 v[50:53], v[172:175], v[180:183], v[50:53]
	v_mfma_f32_16x16x32_bf16 v[38:41], v[164:167], v[188:191], v[38:41]
	v_mfma_f32_16x16x32_bf16 v[34:37], v[172:175], v[188:191], v[34:37]
	v_mfma_f32_16x16x32_bf16 v[22:25], v[164:167], v[196:199], v[22:25]
	v_mfma_f32_16x16x32_bf16 v[18:21], v[172:175], v[196:199], v[18:21]
	v_mfma_f32_16x16x32_bf16 v[6:9], v[164:167], v[204:207], v[6:9]
	v_mfma_f32_16x16x32_bf16 v[2:5], v[172:175], v[204:207], v[2:5]
	v_mfma_f32_16x16x32_bf16 v[54:57], v[168:171], v[184:187], v[54:57]
	v_mfma_f32_16x16x32_bf16 v[50:53], v[176:179], v[184:187], v[50:53]
	v_mfma_f32_16x16x32_bf16 v[38:41], v[168:171], v[192:195], v[38:41]
	v_mfma_f32_16x16x32_bf16 v[34:37], v[176:179], v[192:195], v[34:37]
	v_mfma_f32_16x16x32_bf16 v[22:25], v[168:171], v[200:203], v[22:25]
	v_mfma_f32_16x16x32_bf16 v[18:21], v[176:179], v[200:203], v[18:21]
	v_mfma_f32_16x16x32_bf16 v[6:9], v[168:171], v[208:211], v[6:9]
	v_mfma_f32_16x16x32_bf16 v[2:5], v[176:179], v[208:211], v[2:5]
	s_barrier
	s_add_i32 s57, 0, 0x18000
	s_add_i32 s58, 0, 0x1c000
	v_add_u32_e32 v160, s57, v149
	v_add_u32_e32 v176, s58, v149
	ds_read_b128 v[142:145], v160
	ds_read_b128 v[152:155], v160 offset:1024
	ds_read_b128 v[156:159], v160 offset:2048
	ds_read_b128 v[160:163], v160 offset:3072
	ds_read_b128 v[164:167], v176
	ds_read_b128 v[168:171], v176 offset:1024
	ds_read_b128 v[172:175], v176 offset:2048
	ds_read_b128 v[176:179], v176 offset:3072
	s_add_u32 s22, s28, 0x2b0000
	s_addc_u32 s23, s29, 0
	s_mov_b32 m0, s45
	v_lshl_add_u64 v[220:221], s[22:23], 0, v[136:137]
	ds_read_b128 v[180:183], v151 offset:32768
	ds_read_b128 v[184:187], v151 offset:33792
	ds_read_b128 v[188:191], v151 offset:34816
	ds_read_b128 v[192:195], v151 offset:35840
	ds_read_b128 v[196:199], v151 offset:36864
	ds_read_b128 v[200:203], v151 offset:37888
	ds_read_b128 v[204:207], v151 offset:38912
	ds_read_b128 v[208:211], v151 offset:39936
	global_load_lds_dwordx4 v[220:221], off
	v_lshl_add_u64 v[220:221], s[22:23], 0, v[134:135]
	s_mov_b32 m0, s46
	s_nop 0
	global_load_lds_dwordx4 v[220:221], off
	s_waitcnt vmcnt(8)
	s_waitcnt lgkmcnt(0)
	s_barrier
	s_waitcnt lgkmcnt(0)
	v_mfma_f32_16x16x32_bf16 v[126:129], v[142:145], v[180:183], v[126:129]
	v_mfma_f32_16x16x32_bf16 v[122:125], v[156:159], v[180:183], v[122:125]
	v_mfma_f32_16x16x32_bf16 v[110:113], v[142:145], v[188:191], v[110:113]
	v_mfma_f32_16x16x32_bf16 v[106:109], v[156:159], v[188:191], v[106:109]
	v_mfma_f32_16x16x32_bf16 v[94:97], v[142:145], v[196:199], v[94:97]
	v_mfma_f32_16x16x32_bf16 v[90:93], v[156:159], v[196:199], v[90:93]
	v_mfma_f32_16x16x32_bf16 v[78:81], v[142:145], v[204:207], v[78:81]
	v_mfma_f32_16x16x32_bf16 v[74:77], v[156:159], v[204:207], v[74:77]
	v_mfma_f32_16x16x32_bf16 v[126:129], v[152:155], v[184:187], v[126:129]
	v_mfma_f32_16x16x32_bf16 v[122:125], v[160:163], v[184:187], v[122:125]
	v_mfma_f32_16x16x32_bf16 v[110:113], v[152:155], v[192:195], v[110:113]
	v_mfma_f32_16x16x32_bf16 v[106:109], v[160:163], v[192:195], v[106:109]
	v_mfma_f32_16x16x32_bf16 v[94:97], v[152:155], v[200:203], v[94:97]
	v_mfma_f32_16x16x32_bf16 v[90:93], v[160:163], v[200:203], v[90:93]
	v_mfma_f32_16x16x32_bf16 v[78:81], v[152:155], v[208:211], v[78:81]
	v_mfma_f32_16x16x32_bf16 v[74:77], v[160:163], v[208:211], v[74:77]
	v_mfma_f32_16x16x32_bf16 v[118:121], v[164:167], v[180:183], v[118:121]
	v_mfma_f32_16x16x32_bf16 v[114:117], v[172:175], v[180:183], v[114:117]
	v_mfma_f32_16x16x32_bf16 v[102:105], v[164:167], v[188:191], v[102:105]
	v_mfma_f32_16x16x32_bf16 v[98:101], v[172:175], v[188:191], v[98:101]
	v_mfma_f32_16x16x32_bf16 v[86:89], v[164:167], v[196:199], v[86:89]
	v_mfma_f32_16x16x32_bf16 v[82:85], v[172:175], v[196:199], v[82:85]
	v_mfma_f32_16x16x32_bf16 v[70:73], v[164:167], v[204:207], v[70:73]
	v_mfma_f32_16x16x32_bf16 v[66:69], v[172:175], v[204:207], v[66:69]
	v_mfma_f32_16x16x32_bf16 v[118:121], v[168:171], v[184:187], v[118:121]
	v_mfma_f32_16x16x32_bf16 v[114:117], v[176:179], v[184:187], v[114:117]
	v_mfma_f32_16x16x32_bf16 v[102:105], v[168:171], v[192:195], v[102:105]
	v_mfma_f32_16x16x32_bf16 v[98:101], v[176:179], v[192:195], v[98:101]
	v_mfma_f32_16x16x32_bf16 v[86:89], v[168:171], v[200:203], v[86:89]
	v_mfma_f32_16x16x32_bf16 v[82:85], v[176:179], v[200:203], v[82:85]
	v_mfma_f32_16x16x32_bf16 v[70:73], v[168:171], v[208:211], v[70:73]
	v_mfma_f32_16x16x32_bf16 v[66:69], v[176:179], v[208:211], v[66:69]
	s_barrier
	s_add_i32 s22, s57, s40
	v_lshl_add_u64 v[146:147], v[146:147], 0, s[18:19]
	s_mov_b32 m0, s22
	ds_read_b128 v[180:183], v151 offset:49152
	ds_read_b128 v[184:187], v151 offset:50176
	ds_read_b128 v[188:191], v151 offset:51200
	ds_read_b128 v[192:195], v151 offset:52224
	ds_read_b128 v[196:199], v151 offset:53248
	ds_read_b128 v[200:203], v151 offset:54272
	ds_read_b128 v[204:207], v151 offset:55296
	ds_read_b128 v[208:211], v151 offset:56320
	global_load_lds_dwordx4 v[146:147], off
	s_add_i32 m0, s22, 0x2000
	s_add_u32 s22, s26, 0x2b0080
	v_lshl_add_u64 v[146:147], v[212:213], 0, s[18:19]
	s_addc_u32 s23, s27, 0
	s_add_i32 s26, s58, s40
	global_load_lds_dwordx4 v[146:147], off
	v_lshl_add_u64 v[146:147], s[22:23], 0, v[130:131]
	s_mov_b32 m0, s26
	s_nop 0
	global_load_lds_dwordx4 v[146:147], off
	v_lshl_add_u64 v[146:147], s[22:23], 0, v[132:133]
	s_add_i32 m0, s26, 0x2000
	s_nop 0
	global_load_lds_dwordx4 v[146:147], off
	v_lshl_add_u64 v[146:147], v[216:217], 0, s[18:19]
	s_mov_b32 m0, s47
	s_nop 0
	global_load_lds_dwordx4 v[146:147], off
	v_lshl_add_u64 v[146:147], v[218:219], 0, s[18:19]
	s_mov_b32 m0, s48
	s_nop 0
	global_load_lds_dwordx4 v[146:147], off
	s_waitcnt vmcnt(8)
	s_waitcnt lgkmcnt(0)
	s_barrier
	s_waitcnt lgkmcnt(0)
	v_mfma_f32_16x16x32_bf16 v[62:65], v[142:145], v[180:183], v[62:65]
	v_mfma_f32_16x16x32_bf16 v[58:61], v[156:159], v[180:183], v[58:61]
	v_mfma_f32_16x16x32_bf16 v[46:49], v[142:145], v[188:191], v[46:49]
	v_mfma_f32_16x16x32_bf16 v[42:45], v[156:159], v[188:191], v[42:45]
	v_mfma_f32_16x16x32_bf16 v[30:33], v[142:145], v[196:199], v[30:33]
	v_mfma_f32_16x16x32_bf16 v[26:29], v[156:159], v[196:199], v[26:29]
	v_mfma_f32_16x16x32_bf16 v[14:17], v[142:145], v[204:207], v[14:17]
	v_mfma_f32_16x16x32_bf16 v[10:13], v[156:159], v[204:207], v[10:13]
	v_mfma_f32_16x16x32_bf16 v[62:65], v[152:155], v[184:187], v[62:65]
	v_mfma_f32_16x16x32_bf16 v[58:61], v[160:163], v[184:187], v[58:61]
	v_mfma_f32_16x16x32_bf16 v[46:49], v[152:155], v[192:195], v[46:49]
	v_mfma_f32_16x16x32_bf16 v[42:45], v[160:163], v[192:195], v[42:45]
	v_mfma_f32_16x16x32_bf16 v[30:33], v[152:155], v[200:203], v[30:33]
	v_mfma_f32_16x16x32_bf16 v[26:29], v[160:163], v[200:203], v[26:29]
	v_mfma_f32_16x16x32_bf16 v[14:17], v[152:155], v[208:211], v[14:17]
	v_mfma_f32_16x16x32_bf16 v[10:13], v[160:163], v[208:211], v[10:13]
	v_mfma_f32_16x16x32_bf16 v[54:57], v[164:167], v[180:183], v[54:57]
	v_mfma_f32_16x16x32_bf16 v[50:53], v[172:175], v[180:183], v[50:53]
	v_mfma_f32_16x16x32_bf16 v[38:41], v[164:167], v[188:191], v[38:41]
	v_mfma_f32_16x16x32_bf16 v[34:37], v[172:175], v[188:191], v[34:37]
	v_mfma_f32_16x16x32_bf16 v[22:25], v[164:167], v[196:199], v[22:25]
	v_mfma_f32_16x16x32_bf16 v[18:21], v[172:175], v[196:199], v[18:21]
	v_mfma_f32_16x16x32_bf16 v[6:9], v[164:167], v[204:207], v[6:9]
	v_mfma_f32_16x16x32_bf16 v[2:5], v[172:175], v[204:207], v[2:5]
	v_mfma_f32_16x16x32_bf16 v[54:57], v[168:171], v[184:187], v[54:57]
	v_mfma_f32_16x16x32_bf16 v[50:53], v[176:179], v[184:187], v[50:53]
	v_mfma_f32_16x16x32_bf16 v[38:41], v[168:171], v[192:195], v[38:41]
	v_mfma_f32_16x16x32_bf16 v[34:37], v[176:179], v[192:195], v[34:37]
	v_mfma_f32_16x16x32_bf16 v[22:25], v[168:171], v[200:203], v[22:25]
	v_mfma_f32_16x16x32_bf16 v[18:21], v[176:179], v[200:203], v[18:21]
	v_mfma_f32_16x16x32_bf16 v[6:9], v[168:171], v[208:211], v[6:9]
	v_mfma_f32_16x16x32_bf16 v[2:5], v[176:179], v[208:211], v[2:5]
	s_barrier
	s_add_i32 s56, s56, 2
	s_add_u32 s54, s54, 0x100
	s_addc_u32 s55, s55, 0
	s_cmpk_gt_u32 s56, 0xa9
	s_mov_b64 s[22:23], s[24:25]
	s_cbranch_scc0 .LBB0_1328
	s_and_b64 vcc, exec, s[12:13]
	s_cbranch_vccz .LBB0_1331
	s_barrier

.LBB0_1354:
	s_add_u32 s24, s22, 0x100
	s_addc_u32 s25, s23, 0
	s_add_i32 s60, 0, 0x10000
	s_cmpk_eq_i32 s59, 0xa8
	s_cselect_b32 s29, s3, s25
	s_cselect_b32 s28, s2, s24
	v_add_u32_e32 v149, s60, v194
	s_cselect_b32 s27, s13, s58
	s_cselect_b32 s26, s12, s57
	s_add_i32 s61, 0, 0x14000
	ds_read_b128 v[132:135], v149
	ds_read_b128 v[150:153], v149 offset:1024
	ds_read_b128 v[154:157], v149 offset:2048
	ds_read_b128 v[158:161], v149 offset:3072
	v_add_u32_e32 v149, s61, v194
	ds_read_b128 v[162:165], v149
	ds_read_b128 v[166:169], v149 offset:1024
	ds_read_b128 v[170:173], v149 offset:2048
	ds_read_b128 v[174:177], v149 offset:3072
	v_lshl_add_u64 v[190:191], s[22:23], 0, v[144:145]
	s_add_i32 m0, s48, 0xc000
	ds_read_b128 v[178:181], v196
	ds_read_b128 v[182:185], v196 offset:1024
	ds_read_b128 v[186:189], v196 offset:2048
	ds_read_b128 v[198:201], v196 offset:3072
	ds_read_b128 v[202:205], v196 offset:4096
	ds_read_b128 v[206:209], v196 offset:5120
	ds_read_b128 v[210:213], v196 offset:6144
	ds_read_b128 v[216:219], v196 offset:7168
	global_load_lds_dwordx4 v[190:191], off
	v_lshl_add_u64 v[190:191], s[22:23], 0, v[146:147]
	s_add_i32 m0, s48, 0xe000
	s_nop 0
	global_load_lds_dwordx4 v[190:191], off
	s_waitcnt vmcnt(8)
	s_waitcnt lgkmcnt(0)
	s_barrier
	s_waitcnt lgkmcnt(0)
	v_mfma_f32_16x16x32_bf16 v[126:129], v[132:135], v[178:181], v[126:129]
	v_mfma_f32_16x16x32_bf16 v[122:125], v[154:157], v[178:181], v[122:125]
	v_mfma_f32_16x16x32_bf16 v[110:113], v[132:135], v[186:189], v[110:113]
	v_mfma_f32_16x16x32_bf16 v[106:109], v[154:157], v[186:189], v[106:109]
	v_mfma_f32_16x16x32_bf16 v[94:97], v[132:135], v[202:205], v[94:97]
	v_mfma_f32_16x16x32_bf16 v[90:93], v[154:157], v[202:205], v[90:93]
	v_mfma_f32_16x16x32_bf16 v[78:81], v[132:135], v[210:213], v[78:81]
	v_mfma_f32_16x16x32_bf16 v[74:77], v[154:157], v[210:213], v[74:77]
	v_mfma_f32_16x16x32_bf16 v[126:129], v[150:153], v[182:185], v[126:129]
	v_mfma_f32_16x16x32_bf16 v[122:125], v[158:161], v[182:185], v[122:125]
	v_mfma_f32_16x16x32_bf16 v[110:113], v[150:153], v[198:201], v[110:113]
	v_mfma_f32_16x16x32_bf16 v[106:109], v[158:161], v[198:201], v[106:109]
	v_mfma_f32_16x16x32_bf16 v[94:97], v[150:153], v[206:209], v[94:97]
	v_mfma_f32_16x16x32_bf16 v[90:93], v[158:161], v[206:209], v[90:93]
	v_mfma_f32_16x16x32_bf16 v[78:81], v[150:153], v[216:219], v[78:81]
	v_mfma_f32_16x16x32_bf16 v[74:77], v[158:161], v[216:219], v[74:77]
	v_mfma_f32_16x16x32_bf16 v[118:121], v[162:165], v[178:181], v[118:121]
	v_mfma_f32_16x16x32_bf16 v[114:117], v[170:173], v[178:181], v[114:117]
	v_mfma_f32_16x16x32_bf16 v[102:105], v[162:165], v[186:189], v[102:105]
	v_mfma_f32_16x16x32_bf16 v[98:101], v[170:173], v[186:189], v[98:101]
	v_mfma_f32_16x16x32_bf16 v[86:89], v[162:165], v[202:205], v[86:89]
	v_mfma_f32_16x16x32_bf16 v[82:85], v[170:173], v[202:205], v[82:85]
	v_mfma_f32_16x16x32_bf16 v[70:73], v[162:165], v[210:213], v[70:73]
	v_mfma_f32_16x16x32_bf16 v[66:69], v[170:173], v[210:213], v[66:69]
	v_mfma_f32_16x16x32_bf16 v[118:121], v[166:169], v[182:185], v[118:121]
	v_mfma_f32_16x16x32_bf16 v[114:117], v[174:177], v[182:185], v[114:117]
	v_mfma_f32_16x16x32_bf16 v[102:105], v[166:169], v[198:201], v[102:105]
	v_mfma_f32_16x16x32_bf16 v[98:101], v[174:177], v[198:201], v[98:101]
	v_mfma_f32_16x16x32_bf16 v[86:89], v[166:169], v[206:209], v[86:89]
	v_mfma_f32_16x16x32_bf16 v[82:85], v[174:177], v[206:209], v[82:85]
	v_mfma_f32_16x16x32_bf16 v[70:73], v[166:169], v[216:219], v[70:73]
	v_mfma_f32_16x16x32_bf16 v[66:69], v[174:177], v[216:219], v[66:69]
	s_barrier
	s_add_i32 s22, s60, s30
	v_lshl_add_u64 v[190:191], s[26:27], 0, v[140:141]
	s_mov_b32 m0, s22
	ds_read_b128 v[178:181], v196 offset:16384
	ds_read_b128 v[182:185], v196 offset:17408
	ds_read_b128 v[186:189], v196 offset:18432
	ds_read_b128 v[198:201], v196 offset:19456
	ds_read_b128 v[202:205], v196 offset:20480
	ds_read_b128 v[206:209], v196 offset:21504
	ds_read_b128 v[210:213], v196 offset:22528
	ds_read_b128 v[216:219], v196 offset:23552
	global_load_lds_dwordx4 v[190:191], off
	s_add_i32 m0, s22, 0x2000
	s_add_u32 s22, s26, 0x2b0000
	v_lshl_add_u64 v[220:221], s[26:27], 0, v[136:137]
	s_addc_u32 s23, s27, 0
	s_add_i32 s60, s61, s30
	global_load_lds_dwordx4 v[220:221], off
	v_lshl_add_u64 v[222:223], s[22:23], 0, v[140:141]
	s_mov_b32 m0, s60
	v_lshl_add_u64 v[224:225], s[28:29], 0, v[138:139]
	global_load_lds_dwordx4 v[222:223], off
	v_lshl_add_u64 v[222:223], s[22:23], 0, v[136:137]
	s_add_i32 m0, s60, 0x2000
	s_nop 0
	global_load_lds_dwordx4 v[222:223], off
	v_lshl_add_u64 v[222:223], s[28:29], 0, v[142:143]
	s_mov_b32 m0, s48
	s_nop 0
	global_load_lds_dwordx4 v[222:223], off
	s_mov_b32 m0, s49
	s_nop 0
	global_load_lds_dwordx4 v[224:225], off
	s_waitcnt vmcnt(8)
	s_waitcnt lgkmcnt(0)
	s_barrier
	s_waitcnt lgkmcnt(0)
	v_mfma_f32_16x16x32_bf16 v[62:65], v[132:135], v[178:181], v[62:65]
	v_mfma_f32_16x16x32_bf16 v[58:61], v[154:157], v[178:181], v[58:61]
	v_mfma_f32_16x16x32_bf16 v[46:49], v[132:135], v[186:189], v[46:49]
	v_mfma_f32_16x16x32_bf16 v[42:45], v[154:157], v[186:189], v[42:45]
	v_mfma_f32_16x16x32_bf16 v[30:33], v[132:135], v[202:205], v[30:33]
	v_mfma_f32_16x16x32_bf16 v[26:29], v[154:157], v[202:205], v[26:29]
	v_mfma_f32_16x16x32_bf16 v[14:17], v[132:135], v[210:213], v[14:17]
	v_mfma_f32_16x16x32_bf16 v[10:13], v[154:157], v[210:213], v[10:13]
	v_mfma_f32_16x16x32_bf16 v[62:65], v[150:153], v[182:185], v[62:65]
	v_mfma_f32_16x16x32_bf16 v[58:61], v[158:161], v[182:185], v[58:61]
	v_mfma_f32_16x16x32_bf16 v[46:49], v[150:153], v[198:201], v[46:49]
	v_mfma_f32_16x16x32_bf16 v[42:45], v[158:161], v[198:201], v[42:45]
	v_mfma_f32_16x16x32_bf16 v[30:33], v[150:153], v[206:209], v[30:33]
	v_mfma_f32_16x16x32_bf16 v[26:29], v[158:161], v[206:209], v[26:29]
	v_mfma_f32_16x16x32_bf16 v[14:17], v[150:153], v[216:219], v[14:17]
	v_mfma_f32_16x16x32_bf16 v[10:13], v[158:161], v[216:219], v[10:13]
	v_mfma_f32_16x16x32_bf16 v[54:57], v[162:165], v[178:181], v[54:57]
	v_mfma_f32_16x16x32_bf16 v[50:53], v[170:173], v[178:181], v[50:53]
	v_mfma_f32_16x16x32_bf16 v[38:41], v[162:165], v[186:189], v[38:41]
	v_mfma_f32_16x16x32_bf16 v[34:37], v[170:173], v[186:189], v[34:37]
	v_mfma_f32_16x16x32_bf16 v[22:25], v[162:165], v[202:205], v[22:25]
	v_mfma_f32_16x16x32_bf16 v[18:21], v[170:173], v[202:205], v[18:21]
	v_mfma_f32_16x16x32_bf16 v[6:9], v[162:165], v[210:213], v[6:9]
	v_mfma_f32_16x16x32_bf16 v[2:5], v[170:173], v[210:213], v[2:5]
	v_mfma_f32_16x16x32_bf16 v[54:57], v[166:169], v[182:185], v[54:57]
	v_mfma_f32_16x16x32_bf16 v[50:53], v[174:177], v[182:185], v[50:53]
	v_mfma_f32_16x16x32_bf16 v[38:41], v[166:169], v[198:201], v[38:41]
	v_mfma_f32_16x16x32_bf16 v[34:37], v[174:177], v[198:201], v[34:37]
	v_mfma_f32_16x16x32_bf16 v[22:25], v[166:169], v[206:209], v[22:25]
	v_mfma_f32_16x16x32_bf16 v[18:21], v[174:177], v[206:209], v[18:21]
	v_mfma_f32_16x16x32_bf16 v[6:9], v[166:169], v[216:219], v[6:9]
	v_mfma_f32_16x16x32_bf16 v[2:5], v[174:177], v[216:219], v[2:5]
	s_barrier
	s_add_i32 s60, 0, 0x18000
	v_add_u32_e32 v149, s60, v194
	s_add_i32 s61, 0, 0x1c000
	ds_read_b128 v[132:135], v149
	ds_read_b128 v[150:153], v149 offset:1024
	ds_read_b128 v[154:157], v149 offset:2048
	ds_read_b128 v[158:161], v149 offset:3072
	v_add_u32_e32 v149, s61, v194
	ds_read_b128 v[162:165], v149
	ds_read_b128 v[166:169], v149 offset:1024
	ds_read_b128 v[170:173], v149 offset:2048
	ds_read_b128 v[174:177], v149 offset:3072
	s_add_u32 s22, s28, 0x2b0000
	s_addc_u32 s23, s29, 0
	s_mov_b32 m0, s50
	v_lshl_add_u64 v[226:227], s[22:23], 0, v[142:143]
	ds_read_b128 v[178:181], v196 offset:32768
	ds_read_b128 v[182:185], v196 offset:33792
	ds_read_b128 v[186:189], v196 offset:34816
	ds_read_b128 v[198:201], v196 offset:35840
	ds_read_b128 v[202:205], v196 offset:36864
	ds_read_b128 v[206:209], v196 offset:37888
	ds_read_b128 v[210:213], v196 offset:38912
	ds_read_b128 v[216:219], v196 offset:39936
	global_load_lds_dwordx4 v[226:227], off
	v_lshl_add_u64 v[226:227], s[22:23], 0, v[138:139]
	s_mov_b32 m0, s51
	s_nop 0
	global_load_lds_dwordx4 v[226:227], off
	s_waitcnt vmcnt(8)
	s_waitcnt lgkmcnt(0)
	s_barrier
	s_waitcnt lgkmcnt(0)
	v_mfma_f32_16x16x32_bf16 v[126:129], v[132:135], v[178:181], v[126:129]
	v_mfma_f32_16x16x32_bf16 v[122:125], v[154:157], v[178:181], v[122:125]
	v_mfma_f32_16x16x32_bf16 v[110:113], v[132:135], v[186:189], v[110:113]
	v_mfma_f32_16x16x32_bf16 v[106:109], v[154:157], v[186:189], v[106:109]
	v_mfma_f32_16x16x32_bf16 v[94:97], v[132:135], v[202:205], v[94:97]
	v_mfma_f32_16x16x32_bf16 v[90:93], v[154:157], v[202:205], v[90:93]
	v_mfma_f32_16x16x32_bf16 v[78:81], v[132:135], v[210:213], v[78:81]
	v_mfma_f32_16x16x32_bf16 v[74:77], v[154:157], v[210:213], v[74:77]
	v_mfma_f32_16x16x32_bf16 v[126:129], v[150:153], v[182:185], v[126:129]
	v_mfma_f32_16x16x32_bf16 v[122:125], v[158:161], v[182:185], v[122:125]
	v_mfma_f32_16x16x32_bf16 v[110:113], v[150:153], v[198:201], v[110:113]
	v_mfma_f32_16x16x32_bf16 v[106:109], v[158:161], v[198:201], v[106:109]
	v_mfma_f32_16x16x32_bf16 v[94:97], v[150:153], v[206:209], v[94:97]
	v_mfma_f32_16x16x32_bf16 v[90:93], v[158:161], v[206:209], v[90:93]
	v_mfma_f32_16x16x32_bf16 v[78:81], v[150:153], v[216:219], v[78:81]
	v_mfma_f32_16x16x32_bf16 v[74:77], v[158:161], v[216:219], v[74:77]
	v_mfma_f32_16x16x32_bf16 v[118:121], v[162:165], v[178:181], v[118:121]
	v_mfma_f32_16x16x32_bf16 v[114:117], v[170:173], v[178:181], v[114:117]
	v_mfma_f32_16x16x32_bf16 v[102:105], v[162:165], v[186:189], v[102:105]
	v_mfma_f32_16x16x32_bf16 v[98:101], v[170:173], v[186:189], v[98:101]
	v_mfma_f32_16x16x32_bf16 v[86:89], v[162:165], v[202:205], v[86:89]
	v_mfma_f32_16x16x32_bf16 v[82:85], v[170:173], v[202:205], v[82:85]
	v_mfma_f32_16x16x32_bf16 v[70:73], v[162:165], v[210:213], v[70:73]
	v_mfma_f32_16x16x32_bf16 v[66:69], v[170:173], v[210:213], v[66:69]
	v_mfma_f32_16x16x32_bf16 v[118:121], v[166:169], v[182:185], v[118:121]
	v_mfma_f32_16x16x32_bf16 v[114:117], v[174:177], v[182:185], v[114:117]
	v_mfma_f32_16x16x32_bf16 v[102:105], v[166:169], v[198:201], v[102:105]
	v_mfma_f32_16x16x32_bf16 v[98:101], v[174:177], v[198:201], v[98:101]
	v_mfma_f32_16x16x32_bf16 v[86:89], v[166:169], v[206:209], v[86:89]
	v_mfma_f32_16x16x32_bf16 v[82:85], v[174:177], v[206:209], v[82:85]
	v_mfma_f32_16x16x32_bf16 v[70:73], v[166:169], v[216:219], v[70:73]
	v_mfma_f32_16x16x32_bf16 v[66:69], v[174:177], v[216:219], v[66:69]
	s_barrier
	s_add_i32 s22, s60, s30
	v_lshl_add_u64 v[190:191], v[190:191], 0, s[18:19]
	s_mov_b32 m0, s22
	ds_read_b128 v[178:181], v196 offset:49152
	ds_read_b128 v[182:185], v196 offset:50176
	ds_read_b128 v[186:189], v196 offset:51200
	ds_read_b128 v[198:201], v196 offset:52224
	ds_read_b128 v[202:205], v196 offset:53248
	ds_read_b128 v[206:209], v196 offset:54272
	ds_read_b128 v[210:213], v196 offset:55296
	ds_read_b128 v[216:219], v196 offset:56320
	global_load_lds_dwordx4 v[190:191], off
	s_add_i32 m0, s22, 0x2000
	s_add_u32 s22, s26, 0x2b0080
	v_lshl_add_u64 v[190:191], v[220:221], 0, s[18:19]
	s_addc_u32 s23, s27, 0
	s_add_i32 s26, s61, s30
	global_load_lds_dwordx4 v[190:191], off
	v_lshl_add_u64 v[190:191], s[22:23], 0, v[140:141]
	s_mov_b32 m0, s26
	s_nop 0
	global_load_lds_dwordx4 v[190:191], off
	v_lshl_add_u64 v[190:191], s[22:23], 0, v[136:137]
	s_add_i32 m0, s26, 0x2000
	s_nop 0
	global_load_lds_dwordx4 v[190:191], off
	v_lshl_add_u64 v[190:191], v[222:223], 0, s[18:19]
	s_mov_b32 m0, s52
	s_nop 0
	global_load_lds_dwordx4 v[190:191], off
	v_lshl_add_u64 v[190:191], v[224:225], 0, s[18:19]
	s_mov_b32 m0, s53
	s_nop 0
	global_load_lds_dwordx4 v[190:191], off
	s_waitcnt vmcnt(8)
	s_waitcnt lgkmcnt(0)
	s_barrier
	s_waitcnt lgkmcnt(0)
	v_mfma_f32_16x16x32_bf16 v[62:65], v[132:135], v[178:181], v[62:65]
	v_mfma_f32_16x16x32_bf16 v[58:61], v[154:157], v[178:181], v[58:61]
	v_mfma_f32_16x16x32_bf16 v[46:49], v[132:135], v[186:189], v[46:49]
	v_mfma_f32_16x16x32_bf16 v[42:45], v[154:157], v[186:189], v[42:45]
	v_mfma_f32_16x16x32_bf16 v[30:33], v[132:135], v[202:205], v[30:33]
	v_mfma_f32_16x16x32_bf16 v[26:29], v[154:157], v[202:205], v[26:29]
	v_mfma_f32_16x16x32_bf16 v[14:17], v[132:135], v[210:213], v[14:17]
	v_mfma_f32_16x16x32_bf16 v[10:13], v[154:157], v[210:213], v[10:13]
	v_mfma_f32_16x16x32_bf16 v[62:65], v[150:153], v[182:185], v[62:65]
	v_mfma_f32_16x16x32_bf16 v[58:61], v[158:161], v[182:185], v[58:61]
	v_mfma_f32_16x16x32_bf16 v[46:49], v[150:153], v[198:201], v[46:49]
	v_mfma_f32_16x16x32_bf16 v[42:45], v[158:161], v[198:201], v[42:45]
	v_mfma_f32_16x16x32_bf16 v[30:33], v[150:153], v[206:209], v[30:33]
	v_mfma_f32_16x16x32_bf16 v[26:29], v[158:161], v[206:209], v[26:29]
	v_mfma_f32_16x16x32_bf16 v[14:17], v[150:153], v[216:219], v[14:17]
	v_mfma_f32_16x16x32_bf16 v[10:13], v[158:161], v[216:219], v[10:13]
	v_mfma_f32_16x16x32_bf16 v[54:57], v[162:165], v[178:181], v[54:57]
	v_mfma_f32_16x16x32_bf16 v[50:53], v[170:173], v[178:181], v[50:53]
	v_mfma_f32_16x16x32_bf16 v[38:41], v[162:165], v[186:189], v[38:41]
	v_mfma_f32_16x16x32_bf16 v[34:37], v[170:173], v[186:189], v[34:37]
	v_mfma_f32_16x16x32_bf16 v[22:25], v[162:165], v[202:205], v[22:25]
	v_mfma_f32_16x16x32_bf16 v[18:21], v[170:173], v[202:205], v[18:21]
	v_mfma_f32_16x16x32_bf16 v[6:9], v[162:165], v[210:213], v[6:9]
	v_mfma_f32_16x16x32_bf16 v[2:5], v[170:173], v[210:213], v[2:5]
	v_mfma_f32_16x16x32_bf16 v[54:57], v[166:169], v[182:185], v[54:57]
	v_mfma_f32_16x16x32_bf16 v[50:53], v[174:177], v[182:185], v[50:53]
	v_mfma_f32_16x16x32_bf16 v[38:41], v[166:169], v[198:201], v[38:41]
	v_mfma_f32_16x16x32_bf16 v[34:37], v[174:177], v[198:201], v[34:37]
	v_mfma_f32_16x16x32_bf16 v[22:25], v[166:169], v[206:209], v[22:25]
	v_mfma_f32_16x16x32_bf16 v[18:21], v[174:177], v[206:209], v[18:21]
	v_mfma_f32_16x16x32_bf16 v[6:9], v[166:169], v[216:219], v[6:9]
	v_mfma_f32_16x16x32_bf16 v[2:5], v[174:177], v[216:219], v[2:5]
	s_barrier
	s_add_i32 s59, s59, 2
	s_add_u32 s57, s57, 0x100
	s_addc_u32 s58, s58, 0
	s_cmpk_gt_u32 s59, 0xa9
	s_mov_b64 s[22:23], s[24:25]
	s_cbranch_scc0 .LBB0_1354
	s_and_b64 vcc, exec, s[46:47]
	s_cbranch_vccz .LBB0_1357
	s_barrier

.LBB0_1405:
	s_add_u32 s22, s16, 0x100
	s_addc_u32 s23, s17, 0
	s_add_i32 s54, 0, 0x10000
	s_cmpk_eq_i32 s53, 0xa8
	s_cselect_b32 s27, s3, s23
	s_cselect_b32 s26, s2, s22
	v_add_u32_e32 v148, s54, v152
	s_cselect_b32 s25, s13, s52
	s_cselect_b32 s24, s12, s51
	s_add_i32 s55, 0, 0x14000
	ds_read_b128 v[144:147], v148
	ds_read_b128 v[156:159], v148 offset:1024
	ds_read_b128 v[160:163], v148 offset:2048
	ds_read_b128 v[164:167], v148 offset:3072
	v_add_u32_e32 v148, s55, v152
	ds_read_b128 v[168:171], v148
	ds_read_b128 v[172:175], v148 offset:1024
	ds_read_b128 v[176:179], v148 offset:2048
	ds_read_b128 v[180:183], v148 offset:3072
	v_lshl_add_u64 v[148:149], s[16:17], 0, v[140:141]
	s_add_i32 m0, s29, 0xc000
	ds_read_b128 v[184:187], v154
	ds_read_b128 v[188:191], v154 offset:1024
	ds_read_b128 v[192:195], v154 offset:2048
	ds_read_b128 v[196:199], v154 offset:3072
	ds_read_b128 v[200:203], v154 offset:4096
	ds_read_b128 v[204:207], v154 offset:5120
	ds_read_b128 v[208:211], v154 offset:6144
	ds_read_b128 v[216:219], v154 offset:7168
	global_load_lds_dwordx4 v[148:149], off
	v_lshl_add_u64 v[148:149], s[16:17], 0, v[142:143]
	s_add_i32 m0, s29, 0xe000
	s_nop 0
	global_load_lds_dwordx4 v[148:149], off
	s_waitcnt vmcnt(8)
	s_waitcnt lgkmcnt(0)
	s_barrier
	s_waitcnt lgkmcnt(0)
	v_mfma_f32_16x16x32_bf16 v[126:129], v[144:147], v[184:187], v[126:129]
	v_mfma_f32_16x16x32_bf16 v[122:125], v[160:163], v[184:187], v[122:125]
	v_mfma_f32_16x16x32_bf16 v[110:113], v[144:147], v[192:195], v[110:113]
	v_mfma_f32_16x16x32_bf16 v[106:109], v[160:163], v[192:195], v[106:109]
	v_mfma_f32_16x16x32_bf16 v[94:97], v[144:147], v[200:203], v[94:97]
	v_mfma_f32_16x16x32_bf16 v[90:93], v[160:163], v[200:203], v[90:93]
	v_mfma_f32_16x16x32_bf16 v[78:81], v[144:147], v[208:211], v[78:81]
	v_mfma_f32_16x16x32_bf16 v[74:77], v[160:163], v[208:211], v[74:77]
	v_mfma_f32_16x16x32_bf16 v[126:129], v[156:159], v[188:191], v[126:129]
	v_mfma_f32_16x16x32_bf16 v[122:125], v[164:167], v[188:191], v[122:125]
	v_mfma_f32_16x16x32_bf16 v[110:113], v[156:159], v[196:199], v[110:113]
	v_mfma_f32_16x16x32_bf16 v[106:109], v[164:167], v[196:199], v[106:109]
	v_mfma_f32_16x16x32_bf16 v[94:97], v[156:159], v[204:207], v[94:97]
	v_mfma_f32_16x16x32_bf16 v[90:93], v[164:167], v[204:207], v[90:93]
	v_mfma_f32_16x16x32_bf16 v[78:81], v[156:159], v[216:219], v[78:81]
	v_mfma_f32_16x16x32_bf16 v[74:77], v[164:167], v[216:219], v[74:77]
	v_mfma_f32_16x16x32_bf16 v[118:121], v[168:171], v[184:187], v[118:121]
	v_mfma_f32_16x16x32_bf16 v[114:117], v[176:179], v[184:187], v[114:117]
	v_mfma_f32_16x16x32_bf16 v[102:105], v[168:171], v[192:195], v[102:105]
	v_mfma_f32_16x16x32_bf16 v[98:101], v[176:179], v[192:195], v[98:101]
	v_mfma_f32_16x16x32_bf16 v[86:89], v[168:171], v[200:203], v[86:89]
	v_mfma_f32_16x16x32_bf16 v[82:85], v[176:179], v[200:203], v[82:85]
	v_mfma_f32_16x16x32_bf16 v[70:73], v[168:171], v[208:211], v[70:73]
	v_mfma_f32_16x16x32_bf16 v[66:69], v[176:179], v[208:211], v[66:69]
	v_mfma_f32_16x16x32_bf16 v[118:121], v[172:175], v[188:191], v[118:121]
	v_mfma_f32_16x16x32_bf16 v[114:117], v[180:183], v[188:191], v[114:117]
	v_mfma_f32_16x16x32_bf16 v[102:105], v[172:175], v[196:199], v[102:105]
	v_mfma_f32_16x16x32_bf16 v[98:101], v[180:183], v[196:199], v[98:101]
	v_mfma_f32_16x16x32_bf16 v[86:89], v[172:175], v[204:207], v[86:89]
	v_mfma_f32_16x16x32_bf16 v[82:85], v[180:183], v[204:207], v[82:85]
	v_mfma_f32_16x16x32_bf16 v[70:73], v[172:175], v[216:219], v[70:73]
	v_mfma_f32_16x16x32_bf16 v[66:69], v[180:183], v[216:219], v[66:69]
	s_barrier
	s_add_i32 s16, s54, s28
	v_lshl_add_u64 v[148:149], s[24:25], 0, v[130:131]
	s_mov_b32 m0, s16
	ds_read_b128 v[184:187], v154 offset:16384
	ds_read_b128 v[188:191], v154 offset:17408
	ds_read_b128 v[192:195], v154 offset:18432
	ds_read_b128 v[196:199], v154 offset:19456
	ds_read_b128 v[200:203], v154 offset:20480
	ds_read_b128 v[204:207], v154 offset:21504
	ds_read_b128 v[208:211], v154 offset:22528
	ds_read_b128 v[216:219], v154 offset:23552
	global_load_lds_dwordx4 v[148:149], off
	s_add_i32 m0, s16, 0x2000
	s_add_u32 s16, s24, 0x2b0000
	v_lshl_add_u64 v[212:213], s[24:25], 0, v[132:133]
	s_addc_u32 s17, s25, 0
	s_add_i32 s54, s55, s28
	global_load_lds_dwordx4 v[212:213], off
	v_lshl_add_u64 v[220:221], s[16:17], 0, v[130:131]
	s_mov_b32 m0, s54
	v_lshl_add_u64 v[222:223], s[26:27], 0, v[134:135]
	global_load_lds_dwordx4 v[220:221], off
	v_lshl_add_u64 v[220:221], s[16:17], 0, v[132:133]
	s_add_i32 m0, s54, 0x2000
	s_nop 0
	global_load_lds_dwordx4 v[220:221], off
	v_lshl_add_u64 v[220:221], s[26:27], 0, v[136:137]
	s_mov_b32 m0, s29
	s_nop 0
	global_load_lds_dwordx4 v[220:221], off
	s_mov_b32 m0, s30
	s_nop 0
	global_load_lds_dwordx4 v[222:223], off
	s_waitcnt vmcnt(8)
	s_waitcnt lgkmcnt(0)
	s_barrier
	s_waitcnt lgkmcnt(0)
	v_mfma_f32_16x16x32_bf16 v[62:65], v[144:147], v[184:187], v[62:65]
	v_mfma_f32_16x16x32_bf16 v[58:61], v[160:163], v[184:187], v[58:61]
	v_mfma_f32_16x16x32_bf16 v[46:49], v[144:147], v[192:195], v[46:49]
	v_mfma_f32_16x16x32_bf16 v[42:45], v[160:163], v[192:195], v[42:45]
	v_mfma_f32_16x16x32_bf16 v[30:33], v[144:147], v[200:203], v[30:33]
	v_mfma_f32_16x16x32_bf16 v[26:29], v[160:163], v[200:203], v[26:29]
	v_mfma_f32_16x16x32_bf16 v[14:17], v[144:147], v[208:211], v[14:17]
	v_mfma_f32_16x16x32_bf16 v[10:13], v[160:163], v[208:211], v[10:13]
	v_mfma_f32_16x16x32_bf16 v[62:65], v[156:159], v[188:191], v[62:65]
	v_mfma_f32_16x16x32_bf16 v[58:61], v[164:167], v[188:191], v[58:61]
	v_mfma_f32_16x16x32_bf16 v[46:49], v[156:159], v[196:199], v[46:49]
	v_mfma_f32_16x16x32_bf16 v[42:45], v[164:167], v[196:199], v[42:45]
	v_mfma_f32_16x16x32_bf16 v[30:33], v[156:159], v[204:207], v[30:33]
	v_mfma_f32_16x16x32_bf16 v[26:29], v[164:167], v[204:207], v[26:29]
	v_mfma_f32_16x16x32_bf16 v[14:17], v[156:159], v[216:219], v[14:17]
	v_mfma_f32_16x16x32_bf16 v[10:13], v[164:167], v[216:219], v[10:13]
	v_mfma_f32_16x16x32_bf16 v[54:57], v[168:171], v[184:187], v[54:57]
	v_mfma_f32_16x16x32_bf16 v[50:53], v[176:179], v[184:187], v[50:53]
	v_mfma_f32_16x16x32_bf16 v[38:41], v[168:171], v[192:195], v[38:41]
	v_mfma_f32_16x16x32_bf16 v[34:37], v[176:179], v[192:195], v[34:37]
	v_mfma_f32_16x16x32_bf16 v[22:25], v[168:171], v[200:203], v[22:25]
	v_mfma_f32_16x16x32_bf16 v[18:21], v[176:179], v[200:203], v[18:21]
	v_mfma_f32_16x16x32_bf16 v[6:9], v[168:171], v[208:211], v[6:9]
	v_mfma_f32_16x16x32_bf16 v[2:5], v[176:179], v[208:211], v[2:5]
	v_mfma_f32_16x16x32_bf16 v[54:57], v[172:175], v[188:191], v[54:57]
	v_mfma_f32_16x16x32_bf16 v[50:53], v[180:183], v[188:191], v[50:53]
	v_mfma_f32_16x16x32_bf16 v[38:41], v[172:175], v[196:199], v[38:41]
	v_mfma_f32_16x16x32_bf16 v[34:37], v[180:183], v[196:199], v[34:37]
	v_mfma_f32_16x16x32_bf16 v[22:25], v[172:175], v[204:207], v[22:25]
	v_mfma_f32_16x16x32_bf16 v[18:21], v[180:183], v[204:207], v[18:21]
	v_mfma_f32_16x16x32_bf16 v[6:9], v[172:175], v[216:219], v[6:9]
	v_mfma_f32_16x16x32_bf16 v[2:5], v[180:183], v[216:219], v[2:5]
	s_barrier
	s_add_i32 s54, 0, 0x18000
	v_add_u32_e32 v155, s54, v152
	s_add_i32 s55, 0, 0x1c000
	ds_read_b128 v[144:147], v155
	ds_read_b128 v[156:159], v155 offset:1024
	ds_read_b128 v[160:163], v155 offset:2048
	ds_read_b128 v[164:167], v155 offset:3072
	v_add_u32_e32 v155, s55, v152
	ds_read_b128 v[168:171], v155
	ds_read_b128 v[172:175], v155 offset:1024
	ds_read_b128 v[176:179], v155 offset:2048
	ds_read_b128 v[180:183], v155 offset:3072
	s_add_u32 s16, s26, 0x2b0000
	s_addc_u32 s17, s27, 0
	s_mov_b32 m0, s40
	v_lshl_add_u64 v[224:225], s[16:17], 0, v[136:137]
	ds_read_b128 v[184:187], v154 offset:32768
	ds_read_b128 v[188:191], v154 offset:33792
	ds_read_b128 v[192:195], v154 offset:34816
	ds_read_b128 v[196:199], v154 offset:35840
	ds_read_b128 v[200:203], v154 offset:36864
	ds_read_b128 v[204:207], v154 offset:37888
	ds_read_b128 v[208:211], v154 offset:38912
	ds_read_b128 v[216:219], v154 offset:39936
	global_load_lds_dwordx4 v[224:225], off
	v_lshl_add_u64 v[224:225], s[16:17], 0, v[134:135]
	s_mov_b32 m0, s41
	s_nop 0
	global_load_lds_dwordx4 v[224:225], off
	s_waitcnt vmcnt(8)
	s_waitcnt lgkmcnt(0)
	s_barrier
	s_waitcnt lgkmcnt(0)
	v_mfma_f32_16x16x32_bf16 v[126:129], v[144:147], v[184:187], v[126:129]
	v_mfma_f32_16x16x32_bf16 v[122:125], v[160:163], v[184:187], v[122:125]
	v_mfma_f32_16x16x32_bf16 v[110:113], v[144:147], v[192:195], v[110:113]
	v_mfma_f32_16x16x32_bf16 v[106:109], v[160:163], v[192:195], v[106:109]
	v_mfma_f32_16x16x32_bf16 v[94:97], v[144:147], v[200:203], v[94:97]
	v_mfma_f32_16x16x32_bf16 v[90:93], v[160:163], v[200:203], v[90:93]
	v_mfma_f32_16x16x32_bf16 v[78:81], v[144:147], v[208:211], v[78:81]
	v_mfma_f32_16x16x32_bf16 v[74:77], v[160:163], v[208:211], v[74:77]
	v_mfma_f32_16x16x32_bf16 v[126:129], v[156:159], v[188:191], v[126:129]
	v_mfma_f32_16x16x32_bf16 v[122:125], v[164:167], v[188:191], v[122:125]
	v_mfma_f32_16x16x32_bf16 v[110:113], v[156:159], v[196:199], v[110:113]
	v_mfma_f32_16x16x32_bf16 v[106:109], v[164:167], v[196:199], v[106:109]
	v_mfma_f32_16x16x32_bf16 v[94:97], v[156:159], v[204:207], v[94:97]
	v_mfma_f32_16x16x32_bf16 v[90:93], v[164:167], v[204:207], v[90:93]
	v_mfma_f32_16x16x32_bf16 v[78:81], v[156:159], v[216:219], v[78:81]
	v_mfma_f32_16x16x32_bf16 v[74:77], v[164:167], v[216:219], v[74:77]
	v_mfma_f32_16x16x32_bf16 v[118:121], v[168:171], v[184:187], v[118:121]
	v_mfma_f32_16x16x32_bf16 v[114:117], v[176:179], v[184:187], v[114:117]
	v_mfma_f32_16x16x32_bf16 v[102:105], v[168:171], v[192:195], v[102:105]
	v_mfma_f32_16x16x32_bf16 v[98:101], v[176:179], v[192:195], v[98:101]
	v_mfma_f32_16x16x32_bf16 v[86:89], v[168:171], v[200:203], v[86:89]
	v_mfma_f32_16x16x32_bf16 v[82:85], v[176:179], v[200:203], v[82:85]
	v_mfma_f32_16x16x32_bf16 v[70:73], v[168:171], v[208:211], v[70:73]
	v_mfma_f32_16x16x32_bf16 v[66:69], v[176:179], v[208:211], v[66:69]
	v_mfma_f32_16x16x32_bf16 v[118:121], v[172:175], v[188:191], v[118:121]
	v_mfma_f32_16x16x32_bf16 v[114:117], v[180:183], v[188:191], v[114:117]
	v_mfma_f32_16x16x32_bf16 v[102:105], v[172:175], v[196:199], v[102:105]
	v_mfma_f32_16x16x32_bf16 v[98:101], v[180:183], v[196:199], v[98:101]
	v_mfma_f32_16x16x32_bf16 v[86:89], v[172:175], v[204:207], v[86:89]
	v_mfma_f32_16x16x32_bf16 v[82:85], v[180:183], v[204:207], v[82:85]
	v_mfma_f32_16x16x32_bf16 v[70:73], v[172:175], v[216:219], v[70:73]
	v_mfma_f32_16x16x32_bf16 v[66:69], v[180:183], v[216:219], v[66:69]
	s_barrier
	s_add_i32 s16, s54, s28
	v_lshl_add_u64 v[148:149], v[148:149], 0, s[18:19]
	s_mov_b32 m0, s16
	ds_read_b128 v[184:187], v154 offset:49152
	ds_read_b128 v[188:191], v154 offset:50176
	ds_read_b128 v[192:195], v154 offset:51200
	ds_read_b128 v[196:199], v154 offset:52224
	ds_read_b128 v[200:203], v154 offset:53248
	ds_read_b128 v[204:207], v154 offset:54272
	ds_read_b128 v[208:211], v154 offset:55296
	ds_read_b128 v[216:219], v154 offset:56320
	global_load_lds_dwordx4 v[148:149], off
	s_add_i32 m0, s16, 0x2000
	s_add_u32 s16, s24, 0x2b0080
	v_lshl_add_u64 v[148:149], v[212:213], 0, s[18:19]
	s_addc_u32 s17, s25, 0
	s_add_i32 s24, s55, s28
	global_load_lds_dwordx4 v[148:149], off
	v_lshl_add_u64 v[148:149], s[16:17], 0, v[130:131]
	s_mov_b32 m0, s24
	s_nop 0
	global_load_lds_dwordx4 v[148:149], off
	v_lshl_add_u64 v[148:149], s[16:17], 0, v[132:133]
	s_add_i32 m0, s24, 0x2000
	s_nop 0
	global_load_lds_dwordx4 v[148:149], off
	v_lshl_add_u64 v[148:149], v[220:221], 0, s[18:19]
	s_mov_b32 m0, s44
	s_nop 0
	global_load_lds_dwordx4 v[148:149], off
	v_lshl_add_u64 v[148:149], v[222:223], 0, s[18:19]
	s_mov_b32 m0, s45
	s_nop 0
	global_load_lds_dwordx4 v[148:149], off
	s_waitcnt vmcnt(8)
	s_waitcnt lgkmcnt(0)
	s_barrier
	s_waitcnt lgkmcnt(0)
	v_mfma_f32_16x16x32_bf16 v[62:65], v[144:147], v[184:187], v[62:65]
	v_mfma_f32_16x16x32_bf16 v[58:61], v[160:163], v[184:187], v[58:61]
	v_mfma_f32_16x16x32_bf16 v[46:49], v[144:147], v[192:195], v[46:49]
	v_mfma_f32_16x16x32_bf16 v[42:45], v[160:163], v[192:195], v[42:45]
	v_mfma_f32_16x16x32_bf16 v[30:33], v[144:147], v[200:203], v[30:33]
	v_mfma_f32_16x16x32_bf16 v[26:29], v[160:163], v[200:203], v[26:29]
	v_mfma_f32_16x16x32_bf16 v[14:17], v[144:147], v[208:211], v[14:17]
	v_mfma_f32_16x16x32_bf16 v[10:13], v[160:163], v[208:211], v[10:13]
	v_mfma_f32_16x16x32_bf16 v[62:65], v[156:159], v[188:191], v[62:65]
	v_mfma_f32_16x16x32_bf16 v[58:61], v[164:167], v[188:191], v[58:61]
	v_mfma_f32_16x16x32_bf16 v[46:49], v[156:159], v[196:199], v[46:49]
	v_mfma_f32_16x16x32_bf16 v[42:45], v[164:167], v[196:199], v[42:45]
	v_mfma_f32_16x16x32_bf16 v[30:33], v[156:159], v[204:207], v[30:33]
	v_mfma_f32_16x16x32_bf16 v[26:29], v[164:167], v[204:207], v[26:29]
	v_mfma_f32_16x16x32_bf16 v[14:17], v[156:159], v[216:219], v[14:17]
	v_mfma_f32_16x16x32_bf16 v[10:13], v[164:167], v[216:219], v[10:13]
	v_mfma_f32_16x16x32_bf16 v[54:57], v[168:171], v[184:187], v[54:57]
	v_mfma_f32_16x16x32_bf16 v[50:53], v[176:179], v[184:187], v[50:53]
	v_mfma_f32_16x16x32_bf16 v[38:41], v[168:171], v[192:195], v[38:41]
	v_mfma_f32_16x16x32_bf16 v[34:37], v[176:179], v[192:195], v[34:37]
	v_mfma_f32_16x16x32_bf16 v[22:25], v[168:171], v[200:203], v[22:25]
	v_mfma_f32_16x16x32_bf16 v[18:21], v[176:179], v[200:203], v[18:21]
	v_mfma_f32_16x16x32_bf16 v[6:9], v[168:171], v[208:211], v[6:9]
	v_mfma_f32_16x16x32_bf16 v[2:5], v[176:179], v[208:211], v[2:5]
	v_mfma_f32_16x16x32_bf16 v[54:57], v[172:175], v[188:191], v[54:57]
	v_mfma_f32_16x16x32_bf16 v[50:53], v[180:183], v[188:191], v[50:53]
	v_mfma_f32_16x16x32_bf16 v[38:41], v[172:175], v[196:199], v[38:41]
	v_mfma_f32_16x16x32_bf16 v[34:37], v[180:183], v[196:199], v[34:37]
	v_mfma_f32_16x16x32_bf16 v[22:25], v[172:175], v[204:207], v[22:25]
	v_mfma_f32_16x16x32_bf16 v[18:21], v[180:183], v[204:207], v[18:21]
	v_mfma_f32_16x16x32_bf16 v[6:9], v[172:175], v[216:219], v[6:9]
	v_mfma_f32_16x16x32_bf16 v[2:5], v[180:183], v[216:219], v[2:5]
	s_barrier
	s_add_i32 s53, s53, 2
	s_add_u32 s51, s51, 0x100
	s_addc_u32 s52, s52, 0
	s_cmpk_gt_u32 s53, 0xa9
	s_mov_b64 s[16:17], s[22:23]
	s_cbranch_scc0 .LBB0_1405
	s_and_b64 vcc, exec, s[6:7]
	s_cbranch_vccz .LBB0_1408
	s_barrier
